# v13 + ple epilogue sigmoid interleaved with stores, sp3 cb1p loads batched, mixB1 MFMA weight fragments preloaded (16 in flight), mixA MFMA loop 2 loads in flight
# baseline (speedup 1.0000x reference)
; __device__ __forceinline__ unsigned pk2(float lo, float hi) { const f32x2v v = {lo, hi}; const bf16x2v r = __builtin_convertvector(v, bf16x2v); return __builtin_bit_cast(unsigned, r); }
; __device__ __forceinline__ float sigm(float x) { return __builtin_amdgcn_rcpf(1.f + __expf(-x)); }
; #define GEMM_EPI_LOOP _Pragma("unroll") for (int ai = 0; ai < 2; ++ai) _Pragma("unroll") for (int m = 0; m < 4; ++m) _Pragma("unroll") for (int bj = 0; bj < 2; ++bj)
; __device__ __forceinline__ void gemm_ple_phase(const bf16_t* a, const bf16_t* wpg, const bf16_t* pp, bf16_t* out, char* lds) {
;     ...
;     GEMM_EPI_LOOP {
;       const int row = tm * 256 + ai * 128 + wr * 64 + m * 16 + fr;
; #pragma unroll
;       for (int n = 0; n < 2; ++n) {
;         const int col = tn * 256 + bj * 128 + wc * 32 + n * 16 + 4 * fq;
;         const u32x2 pv = *(const u32x2*)(pp + (size_t)row * 1024 + col);
;         const f32x4 av = acc[ai][bj][m][n];
;         u32x2 o;
;         o.x = pk2(sigm(av[0]) * __uint_as_float(pv.x << 16), sigm(av[1]) * __uint_as_float(pv.x & 0xffff0000u));
;         o.y = pk2(sigm(av[2]) * __uint_as_float(pv.y << 16), sigm(av[3]) * __uint_as_float(pv.y & 0xffff0000u));
;         *(u32x2*)(out + (size_t)row * 1024 + col) = o;
;       }
.LBB0_71:
	s_mul_i32 s30, s30, 0x80000
	s_lshl_b32 s42, s42, 9
	s_add_u32 s30, s30, s42
	v_readlane_b32 s16, v252, 36
	v_readlane_b32 s17, v252, 37
	v_lshrrev_b32_e32 v131, 1, v179
	v_and_b32_e32 v130, 16, v131
	v_and_b32_e32 v131, 8, v131
	v_lshl_or_b32 v130, v131, 2, v130
	v_and_b32_e32 v131, 0xc0, v179
	v_or_b32_e32 v130, v130, v131
	v_ashrrev_i32_e32 v128, 2, v179
	v_and_b32_e32 v128, 0xffffffc0, v128
	v_and_or_b32 v128, v179, 15, v128
	v_lshl_or_b32 v128, v128, 11, v130
	v_add_u32_e32 v128, s30, v128
	v_mov_b32_e32 v140, v128
	v_add_u32_e32 v141, 0x8000, v128
	v_add_u32_e32 v142, 0x10000, v128
	v_add_u32_e32 v143, 0x18000, v128
	v_add_u32_e32 v144, 0x40000, v128
	v_add_u32_e32 v145, 0x48000, v128
	v_add_u32_e32 v146, 0x50000, v128
	v_add_u32_e32 v147, 0x58000, v128
	global_load_dwordx4 v[134:137], v140, s[84:85]
	global_load_dwordx4 v[148:151], v140, s[84:85] offset:256
	global_load_dwordx4 v[152:155], v141, s[84:85]
	global_load_dwordx4 v[156:159], v141, s[84:85] offset:256
	global_load_dwordx4 v[160:163], v142, s[84:85]
	global_load_dwordx4 v[164:167], v142, s[84:85] offset:256
	global_load_dwordx4 v[168:171], v143, s[84:85]
	global_load_dwordx4 v[172:175], v143, s[84:85] offset:256
	global_load_dwordx4 v[180:183], v144, s[84:85]
	global_load_dwordx4 v[184:187], v144, s[84:85] offset:256
	global_load_dwordx4 v[188:191], v145, s[84:85]
	global_load_dwordx4 v[192:195], v145, s[84:85] offset:256
	global_load_dwordx4 v[196:199], v146, s[84:85]
	global_load_dwordx4 v[200:203], v146, s[84:85] offset:256
	global_load_dwordx4 v[204:207], v147, s[84:85]
	global_load_dwordx4 v[208:211], v147, s[84:85] offset:256
	v_mul_f32_e32 v124, 0xbfb8aa3b, v124
	v_mul_f32_e32 v125, 0xbfb8aa3b, v125
	v_mul_f32_e32 v126, 0xbfb8aa3b, v126
	v_mul_f32_e32 v127, 0xbfb8aa3b, v127
	v_mul_f32_e32 v120, 0xbfb8aa3b, v120
	v_mul_f32_e32 v121, 0xbfb8aa3b, v121
	v_mul_f32_e32 v122, 0xbfb8aa3b, v122
	v_mul_f32_e32 v123, 0xbfb8aa3b, v123
	v_exp_f32_e32 v124, v124
	v_exp_f32_e32 v125, v125
	v_exp_f32_e32 v126, v126
	v_exp_f32_e32 v127, v127
	v_exp_f32_e32 v120, v120
	v_exp_f32_e32 v121, v121
	v_exp_f32_e32 v122, v122
	v_exp_f32_e32 v123, v123
	v_add_f32_e32 v124, 1.0, v124
	v_add_f32_e32 v125, 1.0, v125
	v_add_f32_e32 v126, 1.0, v126
	v_add_f32_e32 v127, 1.0, v127
	v_add_f32_e32 v120, 1.0, v120
	v_add_f32_e32 v121, 1.0, v121
	v_add_f32_e32 v122, 1.0, v122
	v_add_f32_e32 v123, 1.0, v123
	v_rcp_f32_e32 v124, v124
	v_rcp_f32_e32 v125, v125
	v_rcp_f32_e32 v126, v126
	v_rcp_f32_e32 v127, v127
	v_rcp_f32_e32 v120, v120
	v_rcp_f32_e32 v121, v121
	v_rcp_f32_e32 v122, v122
	v_rcp_f32_e32 v123, v123
	s_waitcnt vmcnt(15)
	v_permlane16_swap_b32_e32 v134, v136
	v_permlane16_swap_b32_e32 v135, v137
	v_lshlrev_b32_e32 v132, 16, v134
	v_and_b32_e32 v134, 0xffff0000, v134
	v_lshlrev_b32_e32 v133, 16, v135
	v_and_b32_e32 v135, 0xffff0000, v135
	v_mul_f32_e32 v124, v124, v132
	v_mul_f32_e32 v125, v125, v134
	v_mul_f32_e32 v126, v126, v133
	v_mul_f32_e32 v127, v127, v135
	v_lshlrev_b32_e32 v132, 16, v136
	v_and_b32_e32 v136, 0xffff0000, v136
	v_lshlrev_b32_e32 v133, 16, v137
	v_and_b32_e32 v137, 0xffff0000, v137
	v_mul_f32_e32 v120, v120, v132
	v_mul_f32_e32 v121, v121, v136
	v_mul_f32_e32 v122, v122, v133
	v_mul_f32_e32 v123, v123, v137
	v_cvt_pk_bf16_f32 v124, v124, v125
	v_cvt_pk_bf16_f32 v125, v126, v127
	v_cvt_pk_bf16_f32 v126, v120, v121
	v_cvt_pk_bf16_f32 v127, v122, v123
	s_nop 1
	v_permlane16_swap_b32_e32 v124, v126
	v_permlane16_swap_b32_e32 v125, v127
	global_store_dwordx4 v140, v[124:127], s[16:17]
	v_mul_f32_e32 v116, 0xbfb8aa3b, v116
	v_mul_f32_e32 v117, 0xbfb8aa3b, v117
	v_mul_f32_e32 v118, 0xbfb8aa3b, v118
	v_mul_f32_e32 v119, 0xbfb8aa3b, v119
	v_mul_f32_e32 v112, 0xbfb8aa3b, v112
	v_mul_f32_e32 v113, 0xbfb8aa3b, v113
	v_mul_f32_e32 v114, 0xbfb8aa3b, v114
	v_mul_f32_e32 v115, 0xbfb8aa3b, v115
	v_exp_f32_e32 v116, v116
	v_exp_f32_e32 v117, v117
	v_exp_f32_e32 v118, v118
	v_exp_f32_e32 v119, v119
	v_exp_f32_e32 v112, v112
	v_exp_f32_e32 v113, v113
	v_exp_f32_e32 v114, v114
	v_exp_f32_e32 v115, v115
	v_add_f32_e32 v116, 1.0, v116
	v_add_f32_e32 v117, 1.0, v117
	v_add_f32_e32 v118, 1.0, v118
	v_add_f32_e32 v119, 1.0, v119
	v_add_f32_e32 v112, 1.0, v112
	v_add_f32_e32 v113, 1.0, v113
	v_add_f32_e32 v114, 1.0, v114
	v_add_f32_e32 v115, 1.0, v115
	v_rcp_f32_e32 v116, v116
	v_rcp_f32_e32 v117, v117
	v_rcp_f32_e32 v118, v118
	v_rcp_f32_e32 v119, v119
	v_rcp_f32_e32 v112, v112
	v_rcp_f32_e32 v113, v113
	v_rcp_f32_e32 v114, v114
	v_rcp_f32_e32 v115, v115
	s_waitcnt vmcnt(15)
	v_permlane16_swap_b32_e32 v148, v150
	v_permlane16_swap_b32_e32 v149, v151
	v_lshlrev_b32_e32 v132, 16, v148
	v_and_b32_e32 v148, 0xffff0000, v148
	v_lshlrev_b32_e32 v133, 16, v149
	v_and_b32_e32 v149, 0xffff0000, v149
	v_mul_f32_e32 v116, v116, v132
	v_mul_f32_e32 v117, v117, v148
	v_mul_f32_e32 v118, v118, v133
	v_mul_f32_e32 v119, v119, v149
	v_lshlrev_b32_e32 v132, 16, v150
	v_and_b32_e32 v150, 0xffff0000, v150
	v_lshlrev_b32_e32 v133, 16, v151
	v_and_b32_e32 v151, 0xffff0000, v151
	v_mul_f32_e32 v112, v112, v132
	v_mul_f32_e32 v113, v113, v150
	v_mul_f32_e32 v114, v114, v133
	v_mul_f32_e32 v115, v115, v151
	v_cvt_pk_bf16_f32 v116, v116, v117
	v_cvt_pk_bf16_f32 v117, v118, v119
	v_cvt_pk_bf16_f32 v118, v112, v113
	v_cvt_pk_bf16_f32 v119, v114, v115
	s_nop 1
	v_permlane16_swap_b32_e32 v116, v118
	v_permlane16_swap_b32_e32 v117, v119
	global_store_dwordx4 v140, v[116:119], s[16:17] offset:256
	v_mul_f32_e32 v108, 0xbfb8aa3b, v108
	v_mul_f32_e32 v109, 0xbfb8aa3b, v109
	v_mul_f32_e32 v110, 0xbfb8aa3b, v110
	v_mul_f32_e32 v111, 0xbfb8aa3b, v111
	v_mul_f32_e32 v104, 0xbfb8aa3b, v104
	v_mul_f32_e32 v105, 0xbfb8aa3b, v105
	v_mul_f32_e32 v106, 0xbfb8aa3b, v106
	v_mul_f32_e32 v107, 0xbfb8aa3b, v107
	v_exp_f32_e32 v108, v108
	v_exp_f32_e32 v109, v109
	v_exp_f32_e32 v110, v110
	v_exp_f32_e32 v111, v111
	v_exp_f32_e32 v104, v104
	v_exp_f32_e32 v105, v105
	v_exp_f32_e32 v106, v106
	v_exp_f32_e32 v107, v107
	v_add_f32_e32 v108, 1.0, v108
	v_add_f32_e32 v109, 1.0, v109
	v_add_f32_e32 v110, 1.0, v110
	v_add_f32_e32 v111, 1.0, v111
	v_add_f32_e32 v104, 1.0, v104
	v_add_f32_e32 v105, 1.0, v105
	v_add_f32_e32 v106, 1.0, v106
	v_add_f32_e32 v107, 1.0, v107
	v_rcp_f32_e32 v108, v108
	v_rcp_f32_e32 v109, v109
	v_rcp_f32_e32 v110, v110
	v_rcp_f32_e32 v111, v111
	v_rcp_f32_e32 v104, v104
	v_rcp_f32_e32 v105, v105
	v_rcp_f32_e32 v106, v106
	v_rcp_f32_e32 v107, v107
	s_waitcnt vmcnt(15)
; __device__ __forceinline__ unsigned pk2(float lo, float hi) { const f32x2v v = {lo, hi}; const bf16x2v r = __builtin_convertvector(v, bf16x2v); return __builtin_bit_cast(unsigned, r); }
; __device__ __forceinline__ float sigm(float x) { return __builtin_amdgcn_rcpf(1.f + __expf(-x)); }
; #define GEMM_EPI_LOOP _Pragma("unroll") for (int ai = 0; ai < 2; ++ai) _Pragma("unroll") for (int m = 0; m < 4; ++m) _Pragma("unroll") for (int bj = 0; bj < 2; ++bj)
; __device__ __forceinline__ void gemm_ple_phase(const bf16_t* a, const bf16_t* wpg, const bf16_t* pp, bf16_t* out, char* lds) {
;     ...
;     GEMM_EPI_LOOP {
;       const int row = tm * 256 + ai * 128 + wr * 64 + m * 16 + fr;
; #pragma unroll
;       for (int n = 0; n < 2; ++n) {
;         const int col = tn * 256 + bj * 128 + wc * 32 + n * 16 + 4 * fq;
;         const u32x2 pv = *(const u32x2*)(pp + (size_t)row * 1024 + col);
;         const f32x4 av = acc[ai][bj][m][n];
;         u32x2 o;
;         o.x = pk2(sigm(av[0]) * __uint_as_float(pv.x << 16), sigm(av[1]) * __uint_as_float(pv.x & 0xffff0000u));
;         o.y = pk2(sigm(av[2]) * __uint_as_float(pv.y << 16), sigm(av[3]) * __uint_as_float(pv.y & 0xffff0000u));
;         *(u32x2*)(out + (size_t)row * 1024 + col) = o;
;       }
	v_permlane16_swap_b32_e32 v152, v154
	v_permlane16_swap_b32_e32 v153, v155
	v_lshlrev_b32_e32 v132, 16, v152
	v_and_b32_e32 v152, 0xffff0000, v152
	v_lshlrev_b32_e32 v133, 16, v153
	v_and_b32_e32 v153, 0xffff0000, v153
	v_mul_f32_e32 v108, v108, v132
	v_mul_f32_e32 v109, v109, v152
	v_mul_f32_e32 v110, v110, v133
	v_mul_f32_e32 v111, v111, v153
	v_lshlrev_b32_e32 v132, 16, v154
	v_and_b32_e32 v154, 0xffff0000, v154
	v_lshlrev_b32_e32 v133, 16, v155
	v_and_b32_e32 v155, 0xffff0000, v155
	v_mul_f32_e32 v104, v104, v132
	v_mul_f32_e32 v105, v105, v154
	v_mul_f32_e32 v106, v106, v133
	v_mul_f32_e32 v107, v107, v155
	v_cvt_pk_bf16_f32 v108, v108, v109
	v_cvt_pk_bf16_f32 v109, v110, v111
	v_cvt_pk_bf16_f32 v110, v104, v105
	v_cvt_pk_bf16_f32 v111, v106, v107
	s_nop 1
	v_permlane16_swap_b32_e32 v108, v110
	v_permlane16_swap_b32_e32 v109, v111
	global_store_dwordx4 v141, v[108:111], s[16:17]
	v_mul_f32_e32 v100, 0xbfb8aa3b, v100
	v_mul_f32_e32 v101, 0xbfb8aa3b, v101
	v_mul_f32_e32 v102, 0xbfb8aa3b, v102
	v_mul_f32_e32 v103, 0xbfb8aa3b, v103
	v_mul_f32_e32 v96, 0xbfb8aa3b, v96
	v_mul_f32_e32 v97, 0xbfb8aa3b, v97
	v_mul_f32_e32 v98, 0xbfb8aa3b, v98
	v_mul_f32_e32 v99, 0xbfb8aa3b, v99
	v_exp_f32_e32 v100, v100
	v_exp_f32_e32 v101, v101
	v_exp_f32_e32 v102, v102
	v_exp_f32_e32 v103, v103
	v_exp_f32_e32 v96, v96
	v_exp_f32_e32 v97, v97
	v_exp_f32_e32 v98, v98
	v_exp_f32_e32 v99, v99
	v_add_f32_e32 v100, 1.0, v100
	v_add_f32_e32 v101, 1.0, v101
	v_add_f32_e32 v102, 1.0, v102
	v_add_f32_e32 v103, 1.0, v103
	v_add_f32_e32 v96, 1.0, v96
	v_add_f32_e32 v97, 1.0, v97
	v_add_f32_e32 v98, 1.0, v98
	v_add_f32_e32 v99, 1.0, v99
	v_rcp_f32_e32 v100, v100
	v_rcp_f32_e32 v101, v101
	v_rcp_f32_e32 v102, v102
	v_rcp_f32_e32 v103, v103
	v_rcp_f32_e32 v96, v96
	v_rcp_f32_e32 v97, v97
	v_rcp_f32_e32 v98, v98
	v_rcp_f32_e32 v99, v99
	s_waitcnt vmcnt(15)
	v_permlane16_swap_b32_e32 v156, v158
	v_permlane16_swap_b32_e32 v157, v159
	v_lshlrev_b32_e32 v132, 16, v156
	v_and_b32_e32 v156, 0xffff0000, v156
	v_lshlrev_b32_e32 v133, 16, v157
	v_and_b32_e32 v157, 0xffff0000, v157
	v_mul_f32_e32 v100, v100, v132
	v_mul_f32_e32 v101, v101, v156
	v_mul_f32_e32 v102, v102, v133
	v_mul_f32_e32 v103, v103, v157
	v_lshlrev_b32_e32 v132, 16, v158
	v_and_b32_e32 v158, 0xffff0000, v158
	v_lshlrev_b32_e32 v133, 16, v159
	v_and_b32_e32 v159, 0xffff0000, v159
	v_mul_f32_e32 v96, v96, v132
	v_mul_f32_e32 v97, v97, v158
	v_mul_f32_e32 v98, v98, v133
	v_mul_f32_e32 v99, v99, v159
	v_cvt_pk_bf16_f32 v100, v100, v101
	v_cvt_pk_bf16_f32 v101, v102, v103
	v_cvt_pk_bf16_f32 v102, v96, v97
	v_cvt_pk_bf16_f32 v103, v98, v99
	s_nop 1
	v_permlane16_swap_b32_e32 v100, v102
	v_permlane16_swap_b32_e32 v101, v103
	global_store_dwordx4 v141, v[100:103], s[16:17] offset:256
	v_mul_f32_e32 v92, 0xbfb8aa3b, v92
	v_mul_f32_e32 v93, 0xbfb8aa3b, v93
	v_mul_f32_e32 v94, 0xbfb8aa3b, v94
	v_mul_f32_e32 v95, 0xbfb8aa3b, v95
	v_mul_f32_e32 v88, 0xbfb8aa3b, v88
	v_mul_f32_e32 v89, 0xbfb8aa3b, v89
	v_mul_f32_e32 v90, 0xbfb8aa3b, v90
	v_mul_f32_e32 v91, 0xbfb8aa3b, v91
	v_exp_f32_e32 v92, v92
	v_exp_f32_e32 v93, v93
	v_exp_f32_e32 v94, v94
	v_exp_f32_e32 v95, v95
	v_exp_f32_e32 v88, v88
	v_exp_f32_e32 v89, v89
	v_exp_f32_e32 v90, v90
	v_exp_f32_e32 v91, v91
	v_add_f32_e32 v92, 1.0, v92
	v_add_f32_e32 v93, 1.0, v93
	v_add_f32_e32 v94, 1.0, v94
	v_add_f32_e32 v95, 1.0, v95
	v_add_f32_e32 v88, 1.0, v88
	v_add_f32_e32 v89, 1.0, v89
	v_add_f32_e32 v90, 1.0, v90
	v_add_f32_e32 v91, 1.0, v91
	v_rcp_f32_e32 v92, v92
	v_rcp_f32_e32 v93, v93
	v_rcp_f32_e32 v94, v94
	v_rcp_f32_e32 v95, v95
	v_rcp_f32_e32 v88, v88
	v_rcp_f32_e32 v89, v89
	v_rcp_f32_e32 v90, v90
	v_rcp_f32_e32 v91, v91
	s_waitcnt vmcnt(15)
	v_permlane16_swap_b32_e32 v160, v162
	v_permlane16_swap_b32_e32 v161, v163
	v_lshlrev_b32_e32 v132, 16, v160
	v_and_b32_e32 v160, 0xffff0000, v160
	v_lshlrev_b32_e32 v133, 16, v161
	v_and_b32_e32 v161, 0xffff0000, v161
	v_mul_f32_e32 v92, v92, v132
	v_mul_f32_e32 v93, v93, v160
	v_mul_f32_e32 v94, v94, v133
	v_mul_f32_e32 v95, v95, v161
	v_lshlrev_b32_e32 v132, 16, v162
	v_and_b32_e32 v162, 0xffff0000, v162
	v_lshlrev_b32_e32 v133, 16, v163
	v_and_b32_e32 v163, 0xffff0000, v163
	v_mul_f32_e32 v88, v88, v132
	v_mul_f32_e32 v89, v89, v162
	v_mul_f32_e32 v90, v90, v133
	v_mul_f32_e32 v91, v91, v163
	v_cvt_pk_bf16_f32 v92, v92, v93
	v_cvt_pk_bf16_f32 v93, v94, v95
	v_cvt_pk_bf16_f32 v94, v88, v89
	v_cvt_pk_bf16_f32 v95, v90, v91
	s_nop 1
	v_permlane16_swap_b32_e32 v92, v94
	v_permlane16_swap_b32_e32 v93, v95
	global_store_dwordx4 v142, v[92:95], s[16:17]
	v_mul_f32_e32 v84, 0xbfb8aa3b, v84
	v_mul_f32_e32 v85, 0xbfb8aa3b, v85
	v_mul_f32_e32 v86, 0xbfb8aa3b, v86
	v_mul_f32_e32 v87, 0xbfb8aa3b, v87
	v_mul_f32_e32 v80, 0xbfb8aa3b, v80
	v_mul_f32_e32 v81, 0xbfb8aa3b, v81
	v_mul_f32_e32 v82, 0xbfb8aa3b, v82
	v_mul_f32_e32 v83, 0xbfb8aa3b, v83
	v_exp_f32_e32 v84, v84
	v_exp_f32_e32 v85, v85
	v_exp_f32_e32 v86, v86
	v_exp_f32_e32 v87, v87
	v_exp_f32_e32 v80, v80
	v_exp_f32_e32 v81, v81
	v_exp_f32_e32 v82, v82
	v_exp_f32_e32 v83, v83
	v_add_f32_e32 v84, 1.0, v84
	v_add_f32_e32 v85, 1.0, v85
	v_add_f32_e32 v86, 1.0, v86
	v_add_f32_e32 v87, 1.0, v87
	v_add_f32_e32 v80, 1.0, v80
	v_add_f32_e32 v81, 1.0, v81
	v_add_f32_e32 v82, 1.0, v82
	v_add_f32_e32 v83, 1.0, v83
	v_rcp_f32_e32 v84, v84
	v_rcp_f32_e32 v85, v85
	v_rcp_f32_e32 v86, v86
	v_rcp_f32_e32 v87, v87
	v_rcp_f32_e32 v80, v80
	v_rcp_f32_e32 v81, v81
	v_rcp_f32_e32 v82, v82
	v_rcp_f32_e32 v83, v83
	s_waitcnt vmcnt(15)
; __device__ __forceinline__ unsigned pk2(float lo, float hi) { const f32x2v v = {lo, hi}; const bf16x2v r = __builtin_convertvector(v, bf16x2v); return __builtin_bit_cast(unsigned, r); }
; __device__ __forceinline__ float sigm(float x) { return __builtin_amdgcn_rcpf(1.f + __expf(-x)); }
; #define GEMM_EPI_LOOP _Pragma("unroll") for (int ai = 0; ai < 2; ++ai) _Pragma("unroll") for (int m = 0; m < 4; ++m) _Pragma("unroll") for (int bj = 0; bj < 2; ++bj)
; __device__ __forceinline__ void gemm_ple_phase(const bf16_t* a, const bf16_t* wpg, const bf16_t* pp, bf16_t* out, char* lds) {
;   gemm_phase(a, 1024, wpg, 1024, 1024, 4, lds, [&](f32x4 (&acc)[2][2][4][2], int tm, int tn) {
;     GEMM_LANE;
;     GEMM_EPI_LOOP {
;       const int row = tm * 256 + ai * 128 + wr * 64 + m * 16 + fr;
; #pragma unroll
;       for (int n = 0; n < 2; ++n) {
;         const int col = tn * 256 + bj * 128 + wc * 32 + n * 16 + 4 * fq;
;         const u32x2 pv = *(const u32x2*)(pp + (size_t)row * 1024 + col);
;         const f32x4 av = acc[ai][bj][m][n];
;         u32x2 o;
;         o.x = pk2(sigm(av[0]) * __uint_as_float(pv.x << 16), sigm(av[1]) * __uint_as_float(pv.x & 0xffff0000u));
;         o.y = pk2(sigm(av[2]) * __uint_as_float(pv.y << 16), sigm(av[3]) * __uint_as_float(pv.y & 0xffff0000u));
;         *(u32x2*)(out + (size_t)row * 1024 + col) = o;
;       }
;     }
;   });
	v_permlane16_swap_b32_e32 v164, v166
	v_permlane16_swap_b32_e32 v165, v167
	v_lshlrev_b32_e32 v132, 16, v164
	v_and_b32_e32 v164, 0xffff0000, v164
	v_lshlrev_b32_e32 v133, 16, v165
	v_and_b32_e32 v165, 0xffff0000, v165
	v_mul_f32_e32 v84, v84, v132
	v_mul_f32_e32 v85, v85, v164
	v_mul_f32_e32 v86, v86, v133
	v_mul_f32_e32 v87, v87, v165
	v_lshlrev_b32_e32 v132, 16, v166
	v_and_b32_e32 v166, 0xffff0000, v166
	v_lshlrev_b32_e32 v133, 16, v167
	v_and_b32_e32 v167, 0xffff0000, v167
	v_mul_f32_e32 v80, v80, v132
	v_mul_f32_e32 v81, v81, v166
	v_mul_f32_e32 v82, v82, v133
	v_mul_f32_e32 v83, v83, v167
	v_cvt_pk_bf16_f32 v84, v84, v85
	v_cvt_pk_bf16_f32 v85, v86, v87
	v_cvt_pk_bf16_f32 v86, v80, v81
	v_cvt_pk_bf16_f32 v87, v82, v83
	s_nop 1
	v_permlane16_swap_b32_e32 v84, v86
	v_permlane16_swap_b32_e32 v85, v87
	global_store_dwordx4 v142, v[84:87], s[16:17] offset:256
	v_mul_f32_e32 v76, 0xbfb8aa3b, v76
	v_mul_f32_e32 v77, 0xbfb8aa3b, v77
	v_mul_f32_e32 v78, 0xbfb8aa3b, v78
	v_mul_f32_e32 v79, 0xbfb8aa3b, v79
	v_mul_f32_e32 v72, 0xbfb8aa3b, v72
	v_mul_f32_e32 v73, 0xbfb8aa3b, v73
	v_mul_f32_e32 v74, 0xbfb8aa3b, v74
	v_mul_f32_e32 v75, 0xbfb8aa3b, v75
	v_exp_f32_e32 v76, v76
	v_exp_f32_e32 v77, v77
	v_exp_f32_e32 v78, v78
	v_exp_f32_e32 v79, v79
	v_exp_f32_e32 v72, v72
	v_exp_f32_e32 v73, v73
	v_exp_f32_e32 v74, v74
	v_exp_f32_e32 v75, v75
	v_add_f32_e32 v76, 1.0, v76
	v_add_f32_e32 v77, 1.0, v77
	v_add_f32_e32 v78, 1.0, v78
	v_add_f32_e32 v79, 1.0, v79
	v_add_f32_e32 v72, 1.0, v72
	v_add_f32_e32 v73, 1.0, v73
	v_add_f32_e32 v74, 1.0, v74
	v_add_f32_e32 v75, 1.0, v75
	v_rcp_f32_e32 v76, v76
	v_rcp_f32_e32 v77, v77
	v_rcp_f32_e32 v78, v78
	v_rcp_f32_e32 v79, v79
	v_rcp_f32_e32 v72, v72
	v_rcp_f32_e32 v73, v73
	v_rcp_f32_e32 v74, v74
	v_rcp_f32_e32 v75, v75
	s_waitcnt vmcnt(15)
	v_permlane16_swap_b32_e32 v168, v170
	v_permlane16_swap_b32_e32 v169, v171
	v_lshlrev_b32_e32 v132, 16, v168
	v_and_b32_e32 v168, 0xffff0000, v168
	v_lshlrev_b32_e32 v133, 16, v169
	v_and_b32_e32 v169, 0xffff0000, v169
	v_mul_f32_e32 v76, v76, v132
	v_mul_f32_e32 v77, v77, v168
	v_mul_f32_e32 v78, v78, v133
	v_mul_f32_e32 v79, v79, v169
	v_lshlrev_b32_e32 v132, 16, v170
	v_and_b32_e32 v170, 0xffff0000, v170
	v_lshlrev_b32_e32 v133, 16, v171
	v_and_b32_e32 v171, 0xffff0000, v171
	v_mul_f32_e32 v72, v72, v132
	v_mul_f32_e32 v73, v73, v170
	v_mul_f32_e32 v74, v74, v133
	v_mul_f32_e32 v75, v75, v171
	v_cvt_pk_bf16_f32 v76, v76, v77
	v_cvt_pk_bf16_f32 v77, v78, v79
	v_cvt_pk_bf16_f32 v78, v72, v73
	v_cvt_pk_bf16_f32 v79, v74, v75
	s_nop 1
	v_permlane16_swap_b32_e32 v76, v78
	v_permlane16_swap_b32_e32 v77, v79
	global_store_dwordx4 v143, v[76:79], s[16:17]
	v_mul_f32_e32 v68, 0xbfb8aa3b, v68
	v_mul_f32_e32 v69, 0xbfb8aa3b, v69
	v_mul_f32_e32 v70, 0xbfb8aa3b, v70
	v_mul_f32_e32 v71, 0xbfb8aa3b, v71
	v_mul_f32_e32 v64, 0xbfb8aa3b, v64
	v_mul_f32_e32 v65, 0xbfb8aa3b, v65
	v_mul_f32_e32 v66, 0xbfb8aa3b, v66
	v_mul_f32_e32 v67, 0xbfb8aa3b, v67
	v_exp_f32_e32 v68, v68
	v_exp_f32_e32 v69, v69
	v_exp_f32_e32 v70, v70
	v_exp_f32_e32 v71, v71
	v_exp_f32_e32 v64, v64
	v_exp_f32_e32 v65, v65
	v_exp_f32_e32 v66, v66
	v_exp_f32_e32 v67, v67
	v_add_f32_e32 v68, 1.0, v68
	v_add_f32_e32 v69, 1.0, v69
	v_add_f32_e32 v70, 1.0, v70
	v_add_f32_e32 v71, 1.0, v71
	v_add_f32_e32 v64, 1.0, v64
	v_add_f32_e32 v65, 1.0, v65
	v_add_f32_e32 v66, 1.0, v66
	v_add_f32_e32 v67, 1.0, v67
	v_rcp_f32_e32 v68, v68
	v_rcp_f32_e32 v69, v69
	v_rcp_f32_e32 v70, v70
	v_rcp_f32_e32 v71, v71
	v_rcp_f32_e32 v64, v64
	v_rcp_f32_e32 v65, v65
	v_rcp_f32_e32 v66, v66
	v_rcp_f32_e32 v67, v67
	s_waitcnt vmcnt(15)
	v_permlane16_swap_b32_e32 v172, v174
	v_permlane16_swap_b32_e32 v173, v175
	v_lshlrev_b32_e32 v132, 16, v172
	v_and_b32_e32 v172, 0xffff0000, v172
	v_lshlrev_b32_e32 v133, 16, v173
	v_and_b32_e32 v173, 0xffff0000, v173
	v_mul_f32_e32 v68, v68, v132
	v_mul_f32_e32 v69, v69, v172
	v_mul_f32_e32 v70, v70, v133
	v_mul_f32_e32 v71, v71, v173
	v_lshlrev_b32_e32 v132, 16, v174
	v_and_b32_e32 v174, 0xffff0000, v174
	v_lshlrev_b32_e32 v133, 16, v175
	v_and_b32_e32 v175, 0xffff0000, v175
	v_mul_f32_e32 v64, v64, v132
	v_mul_f32_e32 v65, v65, v174
	v_mul_f32_e32 v66, v66, v133
	v_mul_f32_e32 v67, v67, v175
	v_cvt_pk_bf16_f32 v68, v68, v69
	v_cvt_pk_bf16_f32 v69, v70, v71
	v_cvt_pk_bf16_f32 v70, v64, v65
	v_cvt_pk_bf16_f32 v71, v66, v67
	s_nop 1
	v_permlane16_swap_b32_e32 v68, v70
	v_permlane16_swap_b32_e32 v69, v71
	global_store_dwordx4 v143, v[68:71], s[16:17] offset:256
	v_mul_f32_e32 v60, 0xbfb8aa3b, v60
	v_mul_f32_e32 v61, 0xbfb8aa3b, v61
	v_mul_f32_e32 v62, 0xbfb8aa3b, v62
	v_mul_f32_e32 v63, 0xbfb8aa3b, v63
	v_mul_f32_e32 v56, 0xbfb8aa3b, v56
	v_mul_f32_e32 v57, 0xbfb8aa3b, v57
	v_mul_f32_e32 v58, 0xbfb8aa3b, v58
	v_mul_f32_e32 v59, 0xbfb8aa3b, v59
	v_exp_f32_e32 v60, v60
	v_exp_f32_e32 v61, v61
	v_exp_f32_e32 v62, v62
	v_exp_f32_e32 v63, v63
	v_exp_f32_e32 v56, v56
	v_exp_f32_e32 v57, v57
	v_exp_f32_e32 v58, v58
	v_exp_f32_e32 v59, v59
	v_add_f32_e32 v60, 1.0, v60
	v_add_f32_e32 v61, 1.0, v61
	v_add_f32_e32 v62, 1.0, v62
	v_add_f32_e32 v63, 1.0, v63
	v_add_f32_e32 v56, 1.0, v56
	v_add_f32_e32 v57, 1.0, v57
	v_add_f32_e32 v58, 1.0, v58
	v_add_f32_e32 v59, 1.0, v59
	v_rcp_f32_e32 v60, v60
	v_rcp_f32_e32 v61, v61
	v_rcp_f32_e32 v62, v62
	v_rcp_f32_e32 v63, v63
	v_rcp_f32_e32 v56, v56
	v_rcp_f32_e32 v57, v57
	v_rcp_f32_e32 v58, v58
	v_rcp_f32_e32 v59, v59
	s_waitcnt vmcnt(15)
; __device__ __forceinline__ unsigned pk2(float lo, float hi) { const f32x2v v = {lo, hi}; const bf16x2v r = __builtin_convertvector(v, bf16x2v); return __builtin_bit_cast(unsigned, r); }
; __device__ __forceinline__ float sigm(float x) { return __builtin_amdgcn_rcpf(1.f + __expf(-x)); }
; #define GEMM_EPI_LOOP _Pragma("unroll") for (int ai = 0; ai < 2; ++ai) _Pragma("unroll") for (int m = 0; m < 4; ++m) _Pragma("unroll") for (int bj = 0; bj < 2; ++bj)
; __device__ __forceinline__ void gemm_ple_phase(const bf16_t* a, const bf16_t* wpg, const bf16_t* pp, bf16_t* out, char* lds) {
;   gemm_phase(a, 1024, wpg, 1024, 1024, 4, lds, [&](f32x4 (&acc)[2][2][4][2], int tm, int tn) {
;     GEMM_LANE;
;     GEMM_EPI_LOOP {
;       const int row = tm * 256 + ai * 128 + wr * 64 + m * 16 + fr;
; #pragma unroll
;       for (int n = 0; n < 2; ++n) {
;         const int col = tn * 256 + bj * 128 + wc * 32 + n * 16 + 4 * fq;
;         const u32x2 pv = *(const u32x2*)(pp + (size_t)row * 1024 + col);
;         const f32x4 av = acc[ai][bj][m][n];
;         u32x2 o;
;         o.x = pk2(sigm(av[0]) * __uint_as_float(pv.x << 16), sigm(av[1]) * __uint_as_float(pv.x & 0xffff0000u));
;         o.y = pk2(sigm(av[2]) * __uint_as_float(pv.y << 16), sigm(av[3]) * __uint_as_float(pv.y & 0xffff0000u));
;         *(u32x2*)(out + (size_t)row * 1024 + col) = o;
;       }
;     }
;   });
	v_permlane16_swap_b32_e32 v180, v182
	v_permlane16_swap_b32_e32 v181, v183
	v_lshlrev_b32_e32 v132, 16, v180
	v_and_b32_e32 v180, 0xffff0000, v180
	v_lshlrev_b32_e32 v133, 16, v181
	v_and_b32_e32 v181, 0xffff0000, v181
	v_mul_f32_e32 v60, v60, v132
	v_mul_f32_e32 v61, v61, v180
	v_mul_f32_e32 v62, v62, v133
	v_mul_f32_e32 v63, v63, v181
	v_lshlrev_b32_e32 v132, 16, v182
	v_and_b32_e32 v182, 0xffff0000, v182
	v_lshlrev_b32_e32 v133, 16, v183
	v_and_b32_e32 v183, 0xffff0000, v183
	v_mul_f32_e32 v56, v56, v132
	v_mul_f32_e32 v57, v57, v182
	v_mul_f32_e32 v58, v58, v133
	v_mul_f32_e32 v59, v59, v183
	v_cvt_pk_bf16_f32 v60, v60, v61
	v_cvt_pk_bf16_f32 v61, v62, v63
	v_cvt_pk_bf16_f32 v62, v56, v57
	v_cvt_pk_bf16_f32 v63, v58, v59
	s_nop 1
	v_permlane16_swap_b32_e32 v60, v62
	v_permlane16_swap_b32_e32 v61, v63
	global_store_dwordx4 v144, v[60:63], s[16:17]
	v_mul_f32_e32 v52, 0xbfb8aa3b, v52
	v_mul_f32_e32 v53, 0xbfb8aa3b, v53
	v_mul_f32_e32 v54, 0xbfb8aa3b, v54
	v_mul_f32_e32 v55, 0xbfb8aa3b, v55
	v_mul_f32_e32 v48, 0xbfb8aa3b, v48
	v_mul_f32_e32 v49, 0xbfb8aa3b, v49
	v_mul_f32_e32 v50, 0xbfb8aa3b, v50
	v_mul_f32_e32 v51, 0xbfb8aa3b, v51
	v_exp_f32_e32 v52, v52
	v_exp_f32_e32 v53, v53
	v_exp_f32_e32 v54, v54
	v_exp_f32_e32 v55, v55
	v_exp_f32_e32 v48, v48
	v_exp_f32_e32 v49, v49
	v_exp_f32_e32 v50, v50
	v_exp_f32_e32 v51, v51
	v_add_f32_e32 v52, 1.0, v52
	v_add_f32_e32 v53, 1.0, v53
	v_add_f32_e32 v54, 1.0, v54
	v_add_f32_e32 v55, 1.0, v55
	v_add_f32_e32 v48, 1.0, v48
	v_add_f32_e32 v49, 1.0, v49
	v_add_f32_e32 v50, 1.0, v50
	v_add_f32_e32 v51, 1.0, v51
	v_rcp_f32_e32 v52, v52
	v_rcp_f32_e32 v53, v53
	v_rcp_f32_e32 v54, v54
	v_rcp_f32_e32 v55, v55
	v_rcp_f32_e32 v48, v48
	v_rcp_f32_e32 v49, v49
	v_rcp_f32_e32 v50, v50
	v_rcp_f32_e32 v51, v51
	s_waitcnt vmcnt(15)
	v_permlane16_swap_b32_e32 v184, v186
	v_permlane16_swap_b32_e32 v185, v187
	v_lshlrev_b32_e32 v132, 16, v184
	v_and_b32_e32 v184, 0xffff0000, v184
	v_lshlrev_b32_e32 v133, 16, v185
	v_and_b32_e32 v185, 0xffff0000, v185
	v_mul_f32_e32 v52, v52, v132
	v_mul_f32_e32 v53, v53, v184
	v_mul_f32_e32 v54, v54, v133
	v_mul_f32_e32 v55, v55, v185
	v_lshlrev_b32_e32 v132, 16, v186
	v_and_b32_e32 v186, 0xffff0000, v186
	v_lshlrev_b32_e32 v133, 16, v187
	v_and_b32_e32 v187, 0xffff0000, v187
	v_mul_f32_e32 v48, v48, v132
	v_mul_f32_e32 v49, v49, v186
	v_mul_f32_e32 v50, v50, v133
	v_mul_f32_e32 v51, v51, v187
	v_cvt_pk_bf16_f32 v52, v52, v53
	v_cvt_pk_bf16_f32 v53, v54, v55
	v_cvt_pk_bf16_f32 v54, v48, v49
	v_cvt_pk_bf16_f32 v55, v50, v51
	s_nop 1
	v_permlane16_swap_b32_e32 v52, v54
	v_permlane16_swap_b32_e32 v53, v55
	global_store_dwordx4 v144, v[52:55], s[16:17] offset:256
	v_mul_f32_e32 v44, 0xbfb8aa3b, v44
	v_mul_f32_e32 v45, 0xbfb8aa3b, v45
	v_mul_f32_e32 v46, 0xbfb8aa3b, v46
	v_mul_f32_e32 v47, 0xbfb8aa3b, v47
	v_mul_f32_e32 v40, 0xbfb8aa3b, v40
	v_mul_f32_e32 v41, 0xbfb8aa3b, v41
	v_mul_f32_e32 v42, 0xbfb8aa3b, v42
	v_mul_f32_e32 v43, 0xbfb8aa3b, v43
	v_exp_f32_e32 v44, v44
	v_exp_f32_e32 v45, v45
	v_exp_f32_e32 v46, v46
	v_exp_f32_e32 v47, v47
	v_exp_f32_e32 v40, v40
	v_exp_f32_e32 v41, v41
	v_exp_f32_e32 v42, v42
	v_exp_f32_e32 v43, v43
	v_add_f32_e32 v44, 1.0, v44
	v_add_f32_e32 v45, 1.0, v45
	v_add_f32_e32 v46, 1.0, v46
	v_add_f32_e32 v47, 1.0, v47
	v_add_f32_e32 v40, 1.0, v40
	v_add_f32_e32 v41, 1.0, v41
	v_add_f32_e32 v42, 1.0, v42
	v_add_f32_e32 v43, 1.0, v43
	v_rcp_f32_e32 v44, v44
	v_rcp_f32_e32 v45, v45
	v_rcp_f32_e32 v46, v46
	v_rcp_f32_e32 v47, v47
	v_rcp_f32_e32 v40, v40
	v_rcp_f32_e32 v41, v41
	v_rcp_f32_e32 v42, v42
	v_rcp_f32_e32 v43, v43
	s_waitcnt vmcnt(15)
	v_permlane16_swap_b32_e32 v188, v190
	v_permlane16_swap_b32_e32 v189, v191
	v_lshlrev_b32_e32 v132, 16, v188
	v_and_b32_e32 v188, 0xffff0000, v188
	v_lshlrev_b32_e32 v133, 16, v189
	v_and_b32_e32 v189, 0xffff0000, v189
	v_mul_f32_e32 v44, v44, v132
	v_mul_f32_e32 v45, v45, v188
	v_mul_f32_e32 v46, v46, v133
	v_mul_f32_e32 v47, v47, v189
	v_lshlrev_b32_e32 v132, 16, v190
	v_and_b32_e32 v190, 0xffff0000, v190
	v_lshlrev_b32_e32 v133, 16, v191
	v_and_b32_e32 v191, 0xffff0000, v191
	v_mul_f32_e32 v40, v40, v132
	v_mul_f32_e32 v41, v41, v190
	v_mul_f32_e32 v42, v42, v133
	v_mul_f32_e32 v43, v43, v191
	v_cvt_pk_bf16_f32 v44, v44, v45
	v_cvt_pk_bf16_f32 v45, v46, v47
	v_cvt_pk_bf16_f32 v46, v40, v41
	v_cvt_pk_bf16_f32 v47, v42, v43
	s_nop 1
	v_permlane16_swap_b32_e32 v44, v46
	v_permlane16_swap_b32_e32 v45, v47
	global_store_dwordx4 v145, v[44:47], s[16:17]
	v_mul_f32_e32 v36, 0xbfb8aa3b, v36
	v_mul_f32_e32 v37, 0xbfb8aa3b, v37
	v_mul_f32_e32 v38, 0xbfb8aa3b, v38
	v_mul_f32_e32 v39, 0xbfb8aa3b, v39
	v_mul_f32_e32 v32, 0xbfb8aa3b, v32
	v_mul_f32_e32 v33, 0xbfb8aa3b, v33
	v_mul_f32_e32 v34, 0xbfb8aa3b, v34
	v_mul_f32_e32 v35, 0xbfb8aa3b, v35
	v_exp_f32_e32 v36, v36
	v_exp_f32_e32 v37, v37
	v_exp_f32_e32 v38, v38
	v_exp_f32_e32 v39, v39
	v_exp_f32_e32 v32, v32
	v_exp_f32_e32 v33, v33
	v_exp_f32_e32 v34, v34
	v_exp_f32_e32 v35, v35
	v_add_f32_e32 v36, 1.0, v36
	v_add_f32_e32 v37, 1.0, v37
	v_add_f32_e32 v38, 1.0, v38
	v_add_f32_e32 v39, 1.0, v39
	v_add_f32_e32 v32, 1.0, v32
	v_add_f32_e32 v33, 1.0, v33
	v_add_f32_e32 v34, 1.0, v34
	v_add_f32_e32 v35, 1.0, v35
	v_rcp_f32_e32 v36, v36
	v_rcp_f32_e32 v37, v37
	v_rcp_f32_e32 v38, v38
	v_rcp_f32_e32 v39, v39
	v_rcp_f32_e32 v32, v32
	v_rcp_f32_e32 v33, v33
	v_rcp_f32_e32 v34, v34
	v_rcp_f32_e32 v35, v35
	s_waitcnt vmcnt(15)
; __device__ __forceinline__ unsigned pk2(float lo, float hi) { const f32x2v v = {lo, hi}; const bf16x2v r = __builtin_convertvector(v, bf16x2v); return __builtin_bit_cast(unsigned, r); }
; __device__ __forceinline__ float sigm(float x) { return __builtin_amdgcn_rcpf(1.f + __expf(-x)); }
; #define GEMM_EPI_LOOP _Pragma("unroll") for (int ai = 0; ai < 2; ++ai) _Pragma("unroll") for (int m = 0; m < 4; ++m) _Pragma("unroll") for (int bj = 0; bj < 2; ++bj)
; __device__ __forceinline__ void gemm_ple_phase(const bf16_t* a, const bf16_t* wpg, const bf16_t* pp, bf16_t* out, char* lds) {
;   gemm_phase(a, 1024, wpg, 1024, 1024, 4, lds, [&](f32x4 (&acc)[2][2][4][2], int tm, int tn) {
;     GEMM_LANE;
;     GEMM_EPI_LOOP {
;       const int row = tm * 256 + ai * 128 + wr * 64 + m * 16 + fr;
; #pragma unroll
;       for (int n = 0; n < 2; ++n) {
;         const int col = tn * 256 + bj * 128 + wc * 32 + n * 16 + 4 * fq;
;         const u32x2 pv = *(const u32x2*)(pp + (size_t)row * 1024 + col);
;         const f32x4 av = acc[ai][bj][m][n];
;         u32x2 o;
;         o.x = pk2(sigm(av[0]) * __uint_as_float(pv.x << 16), sigm(av[1]) * __uint_as_float(pv.x & 0xffff0000u));
;         o.y = pk2(sigm(av[2]) * __uint_as_float(pv.y << 16), sigm(av[3]) * __uint_as_float(pv.y & 0xffff0000u));
;         *(u32x2*)(out + (size_t)row * 1024 + col) = o;
;       }
;     }
;   });
	v_permlane16_swap_b32_e32 v192, v194
	v_permlane16_swap_b32_e32 v193, v195
	v_lshlrev_b32_e32 v132, 16, v192
	v_and_b32_e32 v192, 0xffff0000, v192
	v_lshlrev_b32_e32 v133, 16, v193
	v_and_b32_e32 v193, 0xffff0000, v193
	v_mul_f32_e32 v36, v36, v132
	v_mul_f32_e32 v37, v37, v192
	v_mul_f32_e32 v38, v38, v133
	v_mul_f32_e32 v39, v39, v193
	v_lshlrev_b32_e32 v132, 16, v194
	v_and_b32_e32 v194, 0xffff0000, v194
	v_lshlrev_b32_e32 v133, 16, v195
	v_and_b32_e32 v195, 0xffff0000, v195
	v_mul_f32_e32 v32, v32, v132
	v_mul_f32_e32 v33, v33, v194
	v_mul_f32_e32 v34, v34, v133
	v_mul_f32_e32 v35, v35, v195
	v_cvt_pk_bf16_f32 v36, v36, v37
	v_cvt_pk_bf16_f32 v37, v38, v39
	v_cvt_pk_bf16_f32 v38, v32, v33
	v_cvt_pk_bf16_f32 v39, v34, v35
	s_nop 1
	v_permlane16_swap_b32_e32 v36, v38
	v_permlane16_swap_b32_e32 v37, v39
	global_store_dwordx4 v145, v[36:39], s[16:17] offset:256
	v_mul_f32_e32 v28, 0xbfb8aa3b, v28
	v_mul_f32_e32 v29, 0xbfb8aa3b, v29
	v_mul_f32_e32 v30, 0xbfb8aa3b, v30
	v_mul_f32_e32 v31, 0xbfb8aa3b, v31
	v_mul_f32_e32 v24, 0xbfb8aa3b, v24
	v_mul_f32_e32 v25, 0xbfb8aa3b, v25
	v_mul_f32_e32 v26, 0xbfb8aa3b, v26
	v_mul_f32_e32 v27, 0xbfb8aa3b, v27
	v_exp_f32_e32 v28, v28
	v_exp_f32_e32 v29, v29
	v_exp_f32_e32 v30, v30
	v_exp_f32_e32 v31, v31
	v_exp_f32_e32 v24, v24
	v_exp_f32_e32 v25, v25
	v_exp_f32_e32 v26, v26
	v_exp_f32_e32 v27, v27
	v_add_f32_e32 v28, 1.0, v28
	v_add_f32_e32 v29, 1.0, v29
	v_add_f32_e32 v30, 1.0, v30
	v_add_f32_e32 v31, 1.0, v31
	v_add_f32_e32 v24, 1.0, v24
	v_add_f32_e32 v25, 1.0, v25
	v_add_f32_e32 v26, 1.0, v26
	v_add_f32_e32 v27, 1.0, v27
	v_rcp_f32_e32 v28, v28
	v_rcp_f32_e32 v29, v29
	v_rcp_f32_e32 v30, v30
	v_rcp_f32_e32 v31, v31
	v_rcp_f32_e32 v24, v24
	v_rcp_f32_e32 v25, v25
	v_rcp_f32_e32 v26, v26
	v_rcp_f32_e32 v27, v27
	s_waitcnt vmcnt(15)
	v_permlane16_swap_b32_e32 v196, v198
	v_permlane16_swap_b32_e32 v197, v199
	v_lshlrev_b32_e32 v132, 16, v196
	v_and_b32_e32 v196, 0xffff0000, v196
	v_lshlrev_b32_e32 v133, 16, v197
	v_and_b32_e32 v197, 0xffff0000, v197
	v_mul_f32_e32 v28, v28, v132
	v_mul_f32_e32 v29, v29, v196
	v_mul_f32_e32 v30, v30, v133
	v_mul_f32_e32 v31, v31, v197
	v_lshlrev_b32_e32 v132, 16, v198
	v_and_b32_e32 v198, 0xffff0000, v198
	v_lshlrev_b32_e32 v133, 16, v199
	v_and_b32_e32 v199, 0xffff0000, v199
	v_mul_f32_e32 v24, v24, v132
	v_mul_f32_e32 v25, v25, v198
	v_mul_f32_e32 v26, v26, v133
	v_mul_f32_e32 v27, v27, v199
	v_cvt_pk_bf16_f32 v28, v28, v29
	v_cvt_pk_bf16_f32 v29, v30, v31
	v_cvt_pk_bf16_f32 v30, v24, v25
	v_cvt_pk_bf16_f32 v31, v26, v27
	s_nop 1
	v_permlane16_swap_b32_e32 v28, v30
	v_permlane16_swap_b32_e32 v29, v31
	global_store_dwordx4 v146, v[28:31], s[16:17]
	v_mul_f32_e32 v20, 0xbfb8aa3b, v20
	v_mul_f32_e32 v21, 0xbfb8aa3b, v21
	v_mul_f32_e32 v22, 0xbfb8aa3b, v22
	v_mul_f32_e32 v23, 0xbfb8aa3b, v23
	v_mul_f32_e32 v16, 0xbfb8aa3b, v16
	v_mul_f32_e32 v17, 0xbfb8aa3b, v17
	v_mul_f32_e32 v18, 0xbfb8aa3b, v18
	v_mul_f32_e32 v19, 0xbfb8aa3b, v19
	v_exp_f32_e32 v20, v20
	v_exp_f32_e32 v21, v21
	v_exp_f32_e32 v22, v22
	v_exp_f32_e32 v23, v23
	v_exp_f32_e32 v16, v16
	v_exp_f32_e32 v17, v17
	v_exp_f32_e32 v18, v18
	v_exp_f32_e32 v19, v19
	v_add_f32_e32 v20, 1.0, v20
	v_add_f32_e32 v21, 1.0, v21
	v_add_f32_e32 v22, 1.0, v22
	v_add_f32_e32 v23, 1.0, v23
	v_add_f32_e32 v16, 1.0, v16
	v_add_f32_e32 v17, 1.0, v17
	v_add_f32_e32 v18, 1.0, v18
	v_add_f32_e32 v19, 1.0, v19
	v_rcp_f32_e32 v20, v20
	v_rcp_f32_e32 v21, v21
	v_rcp_f32_e32 v22, v22
	v_rcp_f32_e32 v23, v23
	v_rcp_f32_e32 v16, v16
	v_rcp_f32_e32 v17, v17
	v_rcp_f32_e32 v18, v18
	v_rcp_f32_e32 v19, v19
	s_waitcnt vmcnt(15)
; __device__ __forceinline__ unsigned pk2(float lo, float hi) { const f32x2v v = {lo, hi}; const bf16x2v r = __builtin_convertvector(v, bf16x2v); return __builtin_bit_cast(unsigned, r); }
; __device__ __forceinline__ float sigm(float x) { return __builtin_amdgcn_rcpf(1.f + __expf(-x)); }
; #define GEMM_EPI_LOOP _Pragma("unroll") for (int ai = 0; ai < 2; ++ai) _Pragma("unroll") for (int m = 0; m < 4; ++m) _Pragma("unroll") for (int bj = 0; bj < 2; ++bj)
; template <class Epi> __device__ __forceinline__ void gemm_phase(const bf16_t* A, int lda, const bf16_t* Bt, int ldb, int K, int TN, char* lds, Epi&& epi) {
;     ...
;     have = it.next();
;     if (have) { f32x4 dummy[2][2][4][2]; gemm_core<true, false>(dummy, A + (size_t)it.tm * 256 * lda, lda, Bt + (size_t)it.tn * 256 * ldb, ldb, K, lds); }
;     epi(acc, tm, tn);
; __device__ __forceinline__ void gemm_ple_phase(const bf16_t* a, const bf16_t* wpg, const bf16_t* pp, bf16_t* out, char* lds) {
;   gemm_phase(a, 1024, wpg, 1024, 1024, 4, lds, [&](f32x4 (&acc)[2][2][4][2], int tm, int tn) {
;     GEMM_LANE;
;     GEMM_EPI_LOOP {
;       const int row = tm * 256 + ai * 128 + wr * 64 + m * 16 + fr;
; #pragma unroll
;       for (int n = 0; n < 2; ++n) {
;         const int col = tn * 256 + bj * 128 + wc * 32 + n * 16 + 4 * fq;
;         const u32x2 pv = *(const u32x2*)(pp + (size_t)row * 1024 + col);
;         const f32x4 av = acc[ai][bj][m][n];
;         u32x2 o;
;         o.x = pk2(sigm(av[0]) * __uint_as_float(pv.x << 16), sigm(av[1]) * __uint_as_float(pv.x & 0xffff0000u));
;         o.y = pk2(sigm(av[2]) * __uint_as_float(pv.y << 16), sigm(av[3]) * __uint_as_float(pv.y & 0xffff0000u));
;         *(u32x2*)(out + (size_t)row * 1024 + col) = o;
;       }
;     }
;   });
	v_permlane16_swap_b32_e32 v200, v202
	v_permlane16_swap_b32_e32 v201, v203
	v_lshlrev_b32_e32 v132, 16, v200
	v_and_b32_e32 v200, 0xffff0000, v200
	v_lshlrev_b32_e32 v133, 16, v201
	v_and_b32_e32 v201, 0xffff0000, v201
	v_mul_f32_e32 v20, v20, v132
	v_mul_f32_e32 v21, v21, v200
	v_mul_f32_e32 v22, v22, v133
	v_mul_f32_e32 v23, v23, v201
	v_lshlrev_b32_e32 v132, 16, v202
	v_and_b32_e32 v202, 0xffff0000, v202
	v_lshlrev_b32_e32 v133, 16, v203
	v_and_b32_e32 v203, 0xffff0000, v203
	v_mul_f32_e32 v16, v16, v132
	v_mul_f32_e32 v17, v17, v202
	v_mul_f32_e32 v18, v18, v133
	v_mul_f32_e32 v19, v19, v203
	v_cvt_pk_bf16_f32 v20, v20, v21
	v_cvt_pk_bf16_f32 v21, v22, v23
	v_cvt_pk_bf16_f32 v22, v16, v17
	v_cvt_pk_bf16_f32 v23, v18, v19
	s_nop 1
	v_permlane16_swap_b32_e32 v20, v22
	v_permlane16_swap_b32_e32 v21, v23
	global_store_dwordx4 v146, v[20:23], s[16:17] offset:256
	v_mul_f32_e32 v12, 0xbfb8aa3b, v12
	v_mul_f32_e32 v13, 0xbfb8aa3b, v13
	v_mul_f32_e32 v14, 0xbfb8aa3b, v14
	v_mul_f32_e32 v15, 0xbfb8aa3b, v15
	v_mul_f32_e32 v8, 0xbfb8aa3b, v8
	v_mul_f32_e32 v9, 0xbfb8aa3b, v9
	v_mul_f32_e32 v10, 0xbfb8aa3b, v10
	v_mul_f32_e32 v11, 0xbfb8aa3b, v11
	v_exp_f32_e32 v12, v12
	v_exp_f32_e32 v13, v13
	v_exp_f32_e32 v14, v14
	v_exp_f32_e32 v15, v15
	v_exp_f32_e32 v8, v8
	v_exp_f32_e32 v9, v9
	v_exp_f32_e32 v10, v10
	v_exp_f32_e32 v11, v11
	v_add_f32_e32 v12, 1.0, v12
	v_add_f32_e32 v13, 1.0, v13
	v_add_f32_e32 v14, 1.0, v14
	v_add_f32_e32 v15, 1.0, v15
	v_add_f32_e32 v8, 1.0, v8
	v_add_f32_e32 v9, 1.0, v9
	v_add_f32_e32 v10, 1.0, v10
	v_add_f32_e32 v11, 1.0, v11
	v_rcp_f32_e32 v12, v12
	v_rcp_f32_e32 v13, v13
	v_rcp_f32_e32 v14, v14
	v_rcp_f32_e32 v15, v15
	v_rcp_f32_e32 v8, v8
	v_rcp_f32_e32 v9, v9
	v_rcp_f32_e32 v10, v10
	v_rcp_f32_e32 v11, v11
	s_waitcnt vmcnt(15)
	v_permlane16_swap_b32_e32 v204, v206
	v_permlane16_swap_b32_e32 v205, v207
	v_lshlrev_b32_e32 v132, 16, v204
	v_and_b32_e32 v204, 0xffff0000, v204
	v_lshlrev_b32_e32 v133, 16, v205
	v_and_b32_e32 v205, 0xffff0000, v205
	v_mul_f32_e32 v12, v12, v132
	v_mul_f32_e32 v13, v13, v204
	v_mul_f32_e32 v14, v14, v133
	v_mul_f32_e32 v15, v15, v205
	v_lshlrev_b32_e32 v132, 16, v206
	v_and_b32_e32 v206, 0xffff0000, v206
	v_lshlrev_b32_e32 v133, 16, v207
	v_and_b32_e32 v207, 0xffff0000, v207
	v_mul_f32_e32 v8, v8, v132
	v_mul_f32_e32 v9, v9, v206
	v_mul_f32_e32 v10, v10, v133
	v_mul_f32_e32 v11, v11, v207
	v_cvt_pk_bf16_f32 v12, v12, v13
	v_cvt_pk_bf16_f32 v13, v14, v15
	v_cvt_pk_bf16_f32 v14, v8, v9
	v_cvt_pk_bf16_f32 v15, v10, v11
	s_nop 1
	v_permlane16_swap_b32_e32 v12, v14
	v_permlane16_swap_b32_e32 v13, v15
	global_store_dwordx4 v147, v[12:15], s[16:17]
	v_mul_f32_e32 v4, 0xbfb8aa3b, v4
	v_mul_f32_e32 v5, 0xbfb8aa3b, v5
	v_mul_f32_e32 v6, 0xbfb8aa3b, v6
	v_mul_f32_e32 v7, 0xbfb8aa3b, v7
	v_mul_f32_e32 v0, 0xbfb8aa3b, v0
	v_mul_f32_e32 v1, 0xbfb8aa3b, v1
	v_mul_f32_e32 v2, 0xbfb8aa3b, v2
	v_mul_f32_e32 v3, 0xbfb8aa3b, v3
	v_exp_f32_e32 v4, v4
	v_exp_f32_e32 v5, v5
	v_exp_f32_e32 v6, v6
	v_exp_f32_e32 v7, v7
	v_exp_f32_e32 v0, v0
	v_exp_f32_e32 v1, v1
	v_exp_f32_e32 v2, v2
	v_exp_f32_e32 v3, v3
	v_add_f32_e32 v4, 1.0, v4
	v_add_f32_e32 v5, 1.0, v5
	v_add_f32_e32 v6, 1.0, v6
	v_add_f32_e32 v7, 1.0, v7
	v_add_f32_e32 v0, 1.0, v0
	v_add_f32_e32 v1, 1.0, v1
	v_add_f32_e32 v2, 1.0, v2
	v_add_f32_e32 v3, 1.0, v3
	v_rcp_f32_e32 v4, v4
	v_rcp_f32_e32 v5, v5
	v_rcp_f32_e32 v6, v6
	v_rcp_f32_e32 v7, v7
	v_rcp_f32_e32 v0, v0
	v_rcp_f32_e32 v1, v1
	v_rcp_f32_e32 v2, v2
	v_rcp_f32_e32 v3, v3
	s_waitcnt vmcnt(15)
	v_permlane16_swap_b32_e32 v208, v210
	v_permlane16_swap_b32_e32 v209, v211
	v_lshlrev_b32_e32 v132, 16, v208
	v_and_b32_e32 v208, 0xffff0000, v208
	v_lshlrev_b32_e32 v133, 16, v209
	v_and_b32_e32 v209, 0xffff0000, v209
	v_mul_f32_e32 v4, v4, v132
	v_mul_f32_e32 v5, v5, v208
	v_mul_f32_e32 v6, v6, v133
	v_mul_f32_e32 v7, v7, v209
	v_lshlrev_b32_e32 v132, 16, v210
	v_and_b32_e32 v210, 0xffff0000, v210
	v_lshlrev_b32_e32 v133, 16, v211
	v_and_b32_e32 v211, 0xffff0000, v211
	v_mul_f32_e32 v0, v0, v132
	v_mul_f32_e32 v1, v1, v210
	v_mul_f32_e32 v2, v2, v133
	v_mul_f32_e32 v3, v3, v211
	v_cvt_pk_bf16_f32 v4, v4, v5
	v_cvt_pk_bf16_f32 v5, v6, v7
	v_cvt_pk_bf16_f32 v6, v0, v1
	v_cvt_pk_bf16_f32 v7, v2, v3
	s_nop 1
	v_permlane16_swap_b32_e32 v4, v6
	v_permlane16_swap_b32_e32 v5, v7
	global_store_dwordx4 v147, v[4:7], s[16:17] offset:256
	s_andn2_b64 vcc, exec, s[38:39]
	s_mov_b32 s42, s34
	s_mov_b32 s30, s36
	s_nop 1
	s_cbranch_vccz .LBB0_86

; __device__ __forceinline__ unsigned pk2(float lo, float hi) { const f32x2v v = {lo, hi}; const bf16x2v r = __builtin_convertvector(v, bf16x2v); return __builtin_bit_cast(unsigned, r); }
; __device__ __forceinline__ float gelu_t(float x) { float u = 0.7978845608028654f * (x + 0.044715f * x * x * x); return x * __builtin_amdgcn_rcpf(1.f + __expf(-2.f * u)); }
; __device__ __forceinline__ f32x4 mfma16(bf16x8 a, bf16x8 b, f32x4 c) { return __builtin_amdgcn_mfma_f32_16x16x32_bf16(a, b, c, 0, 0, 0); }
; __device__ __forceinline__ void mixA_item(const Params& P, int layer, int idx, const bf16_t* z, bf16_t* y, char* lds) {
;     ...
;   for (int ks = 0; ks <= w; ++ks) {
;     bf16x8 wf[2], vf[4];
; #pragma unroll
;     for (int tm = 0; tm < 2; ++tm) wf[tm] = *(const bf16x8*)(W + (size_t)(32 * w + tm * 16 + fr) * 128 + ks * 32 + 8 * fq);
; #pragma unroll
;     for (int dn = 0; dn < 4; ++dn) vf[dn] = *(const bf16x8*)(vT + (dn * 16 + fr) * 136 + ks * 32 + 8 * fq);
; #pragma unroll
;     for (int tm = 0; tm < 2; ++tm)
; #pragma unroll
;       for (int dn = 0; dn < 4; ++dn) acc[tm][dn] = mfma16(vf[dn], wf[tm], acc[tm][dn]);
;   }
; #pragma unroll
;   for (int tm = 0; tm < 2; ++tm) {
;     const int t = 32 * w + tm * 16 + fr;
;     const float bias = P.sgu_b[(layer * 4 + g) * 128 + t];
; #pragma unroll
;     for (int dn = 0; dn < 4; ++dn) {
;       const int d = dn * 16 + 4 * fq;
;       const uint2 uu = *(const uint2*)(z + (size_t)(tok0 + t) * LDZ + ZC_AU + g * 64 + d);
;       const float u0 = gelu_t(__uint_as_float(uu.x << 16)), u1 = gelu_t(__uint_as_float(uu.x & 0xffff0000u)),
;                   u2 = gelu_t(__uint_as_float(uu.y << 16)), u3 = gelu_t(__uint_as_float(uu.y & 0xffff0000u));
;       uint2 o; o.x = pk2(u0 * (acc[tm][dn][0] + bias), u1 * (acc[tm][dn][1] + bias)); o.y = pk2(u2 * (acc[tm][dn][2] + bias), u3 * (acc[tm][dn][3] + bias));
;       *(uint2*)(y + (size_t)(tok0 + t) * 1024 + g * 64 + d) = o;
;     }
.LBB0_551:
	global_load_dwordx4 v[46:49], v[34:35], off
	ds_read_b128 v[50:53], v41
	ds_read_b128 v[54:57], v41 offset:4352
	ds_read_b128 v[62:65], v41 offset:8704
	ds_read_b128 v[66:69], v41 offset:13056
	v_add_co_u32_e32 v58, vcc, s38, v34
	v_add_u32_e32 v44, -1, v44
	s_nop 0
	v_addc_co_u32_e32 v59, vcc, 0, v35, vcc
	global_load_dwordx4 v[84:87], v[58:59], off
	v_cmp_eq_u32_e32 vcc, 0, v44
	v_add_u32_e32 v41, 64, v41
	s_or_b64 s[30:31], vcc, s[30:31]
	v_lshl_add_u64 v[34:35], v[34:35], 0, 64
	s_waitcnt vmcnt(1) lgkmcnt(3)
	v_mfma_f32_16x16x32_bf16 v[28:31], v[50:53], v[46:49], v[28:31]
	s_waitcnt lgkmcnt(2)
	v_mfma_f32_16x16x32_bf16 v[24:27], v[54:57], v[46:49], v[24:27]
	s_waitcnt lgkmcnt(1)
	v_mfma_f32_16x16x32_bf16 v[20:23], v[62:65], v[46:49], v[20:23]
	s_waitcnt lgkmcnt(0)
	v_mfma_f32_16x16x32_bf16 v[16:19], v[66:69], v[46:49], v[16:19]
	s_waitcnt vmcnt(0)
	v_mfma_f32_16x16x32_bf16 v[12:15], v[50:53], v[84:87], v[12:15]
	v_mfma_f32_16x16x32_bf16 v[8:11], v[54:57], v[84:87], v[8:11]
	v_mfma_f32_16x16x32_bf16 v[4:7], v[62:65], v[84:87], v[4:7]
	v_mfma_f32_16x16x32_bf16 v[0:3], v[66:69], v[84:87], v[0:3]
	s_andn2_b64 exec, exec, s[30:31]
	s_cbranch_execnz .LBB0_551
	s_or_b64 exec, exec, s[30:31]
	v_lshl_or_b32 v45, v33, 5, v38
	v_lshlrev_b32_e32 v176, 1, v32
	v_readlane_b32 s30, v252, 34
	v_lshl_add_u64 v[32:33], s[84:85], 0, v[176:177]
	v_readlane_b32 s31, v252, 35
	v_or_b32_e32 v36, v45, v36
	v_lshl_or_b32 v44, v37, 7, s16
	v_lshl_add_u64 v[34:35], s[30:31], 0, v[176:177]
	v_mad_i64_i32 v[46:47], s[30:31], v36, s43, v[32:33]
	v_lshlrev_b32_e32 v176, 3, v40
	v_lshl_add_u64 v[40:41], v[46:47], 0, v[176:177]
	global_load_dwordx2 v[46:47], v[40:41], off
	global_load_dwordx2 v[86:87], v[40:41], off offset:32
	global_load_dwordx2 v[88:89], v[40:41], off offset:64
	global_load_dwordx2 v[90:91], v[40:41], off offset:96
	v_add_co_u32_e32 v92, vcc, 0x14000, v40
	s_nop 1
	v_addc_co_u32_e32 v93, vcc, 0, v41, vcc
	global_load_dwordx2 v[94:95], v[92:93], off
	global_load_dwordx2 v[96:97], v[92:93], off offset:32
	global_load_dwordx2 v[98:99], v[92:93], off offset:64
	global_load_dwordx2 v[100:101], v[92:93], off offset:96
	v_or_b32_e32 v37, v45, v44
	v_readlane_b32 s60, v252, 2
	v_lshlrev_b32_e32 v37, 2, v37
	v_readlane_b32 s66, v252, 8
	v_readlane_b32 s67, v252, 9
	v_readlane_b32 s61, v252, 3
	v_readlane_b32 s62, v252, 4
	v_readlane_b32 s63, v252, 5
	v_readlane_b32 s64, v252, 6
	v_readlane_b32 s65, v252, 7
	global_load_dword v38, v37, s[66:67]
	v_ashrrev_i32_e32 v37, 31, v36
	v_lshlrev_b64 v[48:49], 11, v[36:37]
	v_lshl_add_u64 v[48:49], v[34:35], 0, v[48:49]
	v_readlane_b32 s68, v252, 10
	v_readlane_b32 s69, v252, 11
	v_readlane_b32 s70, v252, 12
	v_readlane_b32 s71, v252, 13
	v_readlane_b32 s72, v252, 14
	v_readlane_b32 s73, v252, 15
	v_readlane_b32 s74, v252, 16
	v_readlane_b32 s75, v252, 17
	s_waitcnt vmcnt(1)
	v_lshlrev_b32_e32 v50, 16, v46
	v_mul_f32_e32 v37, 0x3d372713, v50
	v_mul_f32_e32 v37, v37, v50
	v_mov_b32_e32 v52, v50
	v_fmac_f32_e32 v52, v37, v52
	v_mul_f32_e32 v37, 0x3f4c422a, v52
	v_mul_f32_e32 v37, -2.0, v37
	v_mul_f32_e32 v37, 0x3fb8aa3b, v37
	v_exp_f32_e32 v37, v37
	v_and_b32_e32 v51, 0xffff0000, v46
	v_mov_b32_e32 v53, v51
	s_waitcnt vmcnt(0)
	v_pk_add_f32 v[28:29], v[28:29], v[38:39] op_sel_hi:[1,0]
	v_add_f32_e32 v37, 1.0, v37
	v_rcp_f32_e32 v52, v37
	v_mul_f32_e32 v37, 0x3d372713, v51
	v_mul_f32_e32 v37, v37, v51
	v_fmac_f32_e32 v53, v37, v53
	v_mul_f32_e32 v37, 0x3f4c422a, v53
	v_mul_f32_e32 v37, -2.0, v37
	v_mul_f32_e32 v37, 0x3fb8aa3b, v37
	v_exp_f32_e32 v37, v37
	v_lshlrev_b32_e32 v46, 16, v47
	v_and_b32_e32 v47, 0xffff0000, v47
	v_pk_add_f32 v[30:31], v[30:31], v[38:39] op_sel_hi:[1,0]
	v_add_f32_e32 v37, 1.0, v37
	v_rcp_f32_e32 v53, v37
	v_mov_b32_e32 v37, v47
	v_pk_add_f32 v[24:25], v[24:25], v[38:39] op_sel_hi:[1,0]
	v_pk_add_f32 v[26:27], v[26:27], v[38:39] op_sel_hi:[1,0]
	v_pk_mul_f32 v[50:51], v[52:53], v[50:51]
	v_pk_add_f32 v[20:21], v[20:21], v[38:39] op_sel_hi:[1,0]
	v_pk_mul_f32 v[28:29], v[28:29], v[50:51]
	v_pk_add_f32 v[22:23], v[22:23], v[38:39] op_sel_hi:[1,0]
	v_cvt_pk_bf16_f32 v50, v28, v29
	v_mul_f32_e32 v28, 0x3d372713, v46
	v_mul_f32_e32 v28, v28, v46
	v_mov_b32_e32 v29, v46
	v_fmac_f32_e32 v29, v28, v29
	v_mul_f32_e32 v28, 0x3f4c422a, v29
	v_mul_f32_e32 v29, 0x3d372713, v47
	v_mul_f32_e32 v29, v29, v47
	v_fmac_f32_e32 v37, v29, v37
	v_mul_f32_e32 v29, 0x3f4c422a, v37
	v_mul_f32_e32 v28, -2.0, v28
	v_mul_f32_e32 v29, -2.0, v29
	v_mul_f32_e32 v28, 0x3fb8aa3b, v28
	v_mul_f32_e32 v29, 0x3fb8aa3b, v29
	v_exp_f32_e32 v28, v28
	v_exp_f32_e32 v29, v29
	v_pk_add_f32 v[16:17], v[16:17], v[38:39] op_sel_hi:[1,0]
	v_pk_add_f32 v[18:19], v[18:19], v[38:39] op_sel_hi:[1,0]
	v_add_f32_e32 v28, 1.0, v28
	v_add_f32_e32 v29, 1.0, v29
	v_rcp_f32_e32 v28, v28
	v_rcp_f32_e32 v29, v29
	s_nop 0
	v_pk_mul_f32 v[28:29], v[28:29], v[46:47]
	s_nop 0
	v_pk_mul_f32 v[28:29], v[30:31], v[28:29]
	v_mov_b32_e32 v30, v86
	v_mov_b32_e32 v31, v87
	v_cvt_pk_bf16_f32 v51, v28, v29
	v_lshl_add_u64 v[28:29], v[48:49], 0, v[176:177]
	global_store_dwordx2 v[28:29], v[50:51], off
	v_lshlrev_b32_e32 v46, 16, v30
	v_mul_f32_e32 v37, 0x3d372713, v46
	v_mul_f32_e32 v37, v37, v46
	v_mov_b32_e32 v48, v46
	v_fmac_f32_e32 v48, v37, v48
	v_mul_f32_e32 v37, 0x3f4c422a, v48
	v_mul_f32_e32 v37, -2.0, v37
	v_mul_f32_e32 v37, 0x3fb8aa3b, v37
	v_exp_f32_e32 v37, v37
	v_and_b32_e32 v47, 0xffff0000, v30
	v_mov_b32_e32 v49, v47
	v_lshlrev_b32_e32 v30, 16, v31
	v_add_f32_e32 v37, 1.0, v37
	v_rcp_f32_e32 v48, v37
	v_mul_f32_e32 v37, 0x3d372713, v47
	v_mul_f32_e32 v37, v37, v47
	v_fmac_f32_e32 v49, v37, v49
	v_mul_f32_e32 v37, 0x3f4c422a, v49
; __device__ __forceinline__ unsigned pk2(float lo, float hi) { const f32x2v v = {lo, hi}; const bf16x2v r = __builtin_convertvector(v, bf16x2v); return __builtin_bit_cast(unsigned, r); }
; __device__ __forceinline__ float gelu_t(float x) { float u = 0.7978845608028654f * (x + 0.044715f * x * x * x); return x * __builtin_amdgcn_rcpf(1.f + __expf(-2.f * u)); }
; __device__ __forceinline__ void mixA_item(const Params& P, int layer, int idx, const bf16_t* z, bf16_t* y, char* lds) {
;     ...
;   for (int tm = 0; tm < 2; ++tm) {
;     const int t = 32 * w + tm * 16 + fr;
;     const float bias = P.sgu_b[(layer * 4 + g) * 128 + t];
; #pragma unroll
;     for (int dn = 0; dn < 4; ++dn) {
;       const int d = dn * 16 + 4 * fq;
;       const uint2 uu = *(const uint2*)(z + (size_t)(tok0 + t) * LDZ + ZC_AU + g * 64 + d);
;       const float u0 = gelu_t(__uint_as_float(uu.x << 16)), u1 = gelu_t(__uint_as_float(uu.x & 0xffff0000u)),
;                   u2 = gelu_t(__uint_as_float(uu.y << 16)), u3 = gelu_t(__uint_as_float(uu.y & 0xffff0000u));
;       uint2 o; o.x = pk2(u0 * (acc[tm][dn][0] + bias), u1 * (acc[tm][dn][1] + bias)); o.y = pk2(u2 * (acc[tm][dn][2] + bias), u3 * (acc[tm][dn][3] + bias));
;       *(uint2*)(y + (size_t)(tok0 + t) * 1024 + g * 64 + d) = o;
;     }
;   }
;   __syncthreads();
	v_mul_f32_e32 v37, -2.0, v37
	v_mul_f32_e32 v37, 0x3fb8aa3b, v37
	v_exp_f32_e32 v37, v37
	v_and_b32_e32 v31, 0xffff0000, v31
	v_add_f32_e32 v37, 1.0, v37
	v_rcp_f32_e32 v49, v37
	v_mov_b32_e32 v37, v30
	v_pk_mul_f32 v[46:47], v[48:49], v[46:47]
	s_nop 0
	v_pk_mul_f32 v[24:25], v[24:25], v[46:47]
	s_nop 0
	v_cvt_pk_bf16_f32 v24, v24, v25
	v_mul_f32_e32 v25, 0x3d372713, v30
	v_mul_f32_e32 v25, v25, v30
	v_fmac_f32_e32 v37, v25, v37
	v_mul_f32_e32 v25, 0x3f4c422a, v37
	v_mul_f32_e32 v25, -2.0, v25
	v_mul_f32_e32 v25, 0x3fb8aa3b, v25
	v_exp_f32_e32 v25, v25
	v_mov_b32_e32 v37, v31
	v_add_f32_e32 v25, 1.0, v25
	v_rcp_f32_e32 v46, v25
	v_mul_f32_e32 v25, 0x3d372713, v31
	v_mul_f32_e32 v25, v25, v31
	v_fmac_f32_e32 v37, v25, v37
	v_mul_f32_e32 v25, 0x3f4c422a, v37
	v_mul_f32_e32 v25, -2.0, v25
	v_mul_f32_e32 v25, 0x3fb8aa3b, v25
	v_exp_f32_e32 v25, v25
	s_nop 0
	v_add_f32_e32 v25, 1.0, v25
	v_rcp_f32_e32 v47, v25
	s_nop 0
	v_pk_mul_f32 v[30:31], v[46:47], v[30:31]
	s_nop 0
	v_pk_mul_f32 v[26:27], v[26:27], v[30:31]
	s_nop 0
	v_cvt_pk_bf16_f32 v25, v26, v27
	global_store_dwordx2 v[28:29], v[24:25], off offset:32
	v_mov_b32_e32 v24, v88
	v_mov_b32_e32 v25, v89
	v_lshlrev_b32_e32 v26, 16, v24
	v_mul_f32_e32 v30, 0x3d372713, v26
	v_mul_f32_e32 v30, v30, v26
	v_mov_b32_e32 v31, v26
	v_and_b32_e32 v27, 0xffff0000, v24
	v_fmac_f32_e32 v31, v30, v31
	v_mul_f32_e32 v30, 0x3f4c422a, v31
	v_mul_f32_e32 v31, 0x3d372713, v27
	v_mul_f32_e32 v31, v31, v27
	v_mov_b32_e32 v37, v27
	v_fmac_f32_e32 v37, v31, v37
	v_mul_f32_e32 v31, 0x3f4c422a, v37
	v_mul_f32_e32 v30, -2.0, v30
	v_mul_f32_e32 v31, -2.0, v31
	v_mul_f32_e32 v30, 0x3fb8aa3b, v30
	v_mul_f32_e32 v31, 0x3fb8aa3b, v31
	v_exp_f32_e32 v30, v30
	v_exp_f32_e32 v31, v31
	v_lshlrev_b32_e32 v24, 16, v25
	v_and_b32_e32 v25, 0xffff0000, v25
	v_add_f32_e32 v30, 1.0, v30
	v_add_f32_e32 v31, 1.0, v31
	v_rcp_f32_e32 v30, v30
	v_rcp_f32_e32 v31, v31
	s_nop 0
	v_pk_mul_f32 v[26:27], v[30:31], v[26:27]
	s_nop 0
	v_pk_mul_f32 v[20:21], v[20:21], v[26:27]
	v_mov_b32_e32 v26, v24
	v_cvt_pk_bf16_f32 v20, v20, v21
	v_mul_f32_e32 v21, 0x3d372713, v24
	v_mul_f32_e32 v21, v21, v24
	v_fmac_f32_e32 v26, v21, v26
	v_mul_f32_e32 v21, 0x3f4c422a, v26
	v_mul_f32_e32 v21, -2.0, v21
	v_mul_f32_e32 v21, 0x3fb8aa3b, v21
	v_exp_f32_e32 v21, v21
	v_mov_b32_e32 v27, v25
	v_add_f32_e32 v21, 1.0, v21
	v_rcp_f32_e32 v26, v21
	v_mul_f32_e32 v21, 0x3d372713, v25
	v_mul_f32_e32 v21, v21, v25
	v_fmac_f32_e32 v27, v21, v27
	v_mul_f32_e32 v21, 0x3f4c422a, v27
	v_mul_f32_e32 v21, -2.0, v21
	v_mul_f32_e32 v21, 0x3fb8aa3b, v21
	v_exp_f32_e32 v21, v21
	s_nop 0
	v_add_f32_e32 v21, 1.0, v21
	v_rcp_f32_e32 v27, v21
	s_nop 0
	v_pk_mul_f32 v[24:25], v[26:27], v[24:25]
	s_nop 0
	v_pk_mul_f32 v[22:23], v[22:23], v[24:25]
	s_nop 0
	v_cvt_pk_bf16_f32 v21, v22, v23
	global_store_dwordx2 v[28:29], v[20:21], off offset:64
	v_mov_b32_e32 v20, v90
	v_mov_b32_e32 v21, v91
	v_lshlrev_b32_e32 v22, 16, v20
	v_mul_f32_e32 v24, 0x3d372713, v22
	v_mul_f32_e32 v24, v24, v22
	v_mov_b32_e32 v25, v22
	v_and_b32_e32 v23, 0xffff0000, v20
	v_fmac_f32_e32 v25, v24, v25
	v_mul_f32_e32 v24, 0x3f4c422a, v25
	v_mul_f32_e32 v25, 0x3d372713, v23
	v_mul_f32_e32 v25, v25, v23
	v_mov_b32_e32 v26, v23
	v_fmac_f32_e32 v26, v25, v26
	v_mul_f32_e32 v25, 0x3f4c422a, v26
	v_mul_f32_e32 v24, -2.0, v24
	v_mul_f32_e32 v25, -2.0, v25
	v_mul_f32_e32 v24, 0x3fb8aa3b, v24
	v_mul_f32_e32 v25, 0x3fb8aa3b, v25
	v_exp_f32_e32 v24, v24
	v_exp_f32_e32 v25, v25
	v_lshlrev_b32_e32 v20, 16, v21
	v_and_b32_e32 v21, 0xffff0000, v21
	v_add_f32_e32 v24, 1.0, v24
	v_add_f32_e32 v25, 1.0, v25
	v_rcp_f32_e32 v24, v24
	v_rcp_f32_e32 v25, v25
	s_nop 0
	v_pk_mul_f32 v[22:23], v[24:25], v[22:23]
	s_nop 0
	v_pk_mul_f32 v[16:17], v[16:17], v[22:23]
	v_mov_b32_e32 v22, v20
	v_cvt_pk_bf16_f32 v16, v16, v17
	v_mul_f32_e32 v17, 0x3d372713, v20
	v_mul_f32_e32 v17, v17, v20
	v_fmac_f32_e32 v22, v17, v22
	v_mul_f32_e32 v17, 0x3f4c422a, v22
	v_mul_f32_e32 v17, -2.0, v17
	v_mul_f32_e32 v17, 0x3fb8aa3b, v17
	v_exp_f32_e32 v17, v17
	v_mov_b32_e32 v23, v21
	v_add_f32_e32 v17, 1.0, v17
	v_rcp_f32_e32 v22, v17
	v_mul_f32_e32 v17, 0x3d372713, v21
	v_mul_f32_e32 v17, v17, v21
	v_fmac_f32_e32 v23, v17, v23
	v_mul_f32_e32 v17, 0x3f4c422a, v23
	v_mul_f32_e32 v17, -2.0, v17
	v_mul_f32_e32 v17, 0x3fb8aa3b, v17
	v_exp_f32_e32 v17, v17
	s_nop 0
	v_add_f32_e32 v17, 1.0, v17
	v_rcp_f32_e32 v23, v17
	s_nop 0
	v_pk_mul_f32 v[20:21], v[22:23], v[20:21]
	s_nop 0
	v_pk_mul_f32 v[18:19], v[18:19], v[20:21]
	s_nop 0
	v_cvt_pk_bf16_f32 v17, v18, v19
	v_or_b32_e32 v18, 16, v36
	v_ashrrev_i32_e32 v19, 31, v18
	v_mad_i64_i32 v[20:21], s[30:31], v18, s43, v[32:33]
	v_lshlrev_b64 v[18:19], 11, v[18:19]
	v_lshl_add_u64 v[22:23], v[34:35], 0, v[18:19]
	v_lshl_add_u64 v[18:19], v[20:21], 0, v[176:177]
	v_mov_b32_e32 v20, v94
	v_mov_b32_e32 v21, v95
	v_readlane_b32 s30, v253, 4
	global_store_dwordx2 v[28:29], v[16:17], off offset:96
	v_add_lshl_u32 v16, v45, v44, 2
	global_load_dword v16, v16, s[66:67] offset:64
	v_add_u32_e32 v43, s30, v43
	v_subrev_u16_e32 v42, s30, v42
	s_movk_i32 s30, 0x3ff
	v_readlane_b32 s31, v254, 44
	v_cmp_lt_i32_e32 vcc, s30, v43
	s_or_b64 s[36:37], vcc, s[36:37]
	v_add_u32_e32 v39, s31, v39
	s_waitcnt vmcnt(2)
	v_lshlrev_b32_e32 v24, 16, v20
	v_mul_f32_e32 v17, 0x3d372713, v24
	v_mul_f32_e32 v17, v17, v24
	v_mov_b32_e32 v26, v24
	v_fmac_f32_e32 v26, v17, v26
	v_mul_f32_e32 v17, 0x3f4c422a, v26
	v_mul_f32_e32 v17, -2.0, v17
	v_mul_f32_e32 v17, 0x3fb8aa3b, v17
	v_exp_f32_e32 v17, v17
	v_and_b32_e32 v25, 0xffff0000, v20
	v_mov_b32_e32 v27, v25
	v_lshlrev_b32_e32 v20, 16, v21
	v_add_f32_e32 v17, 1.0, v17
	v_rcp_f32_e32 v26, v17
	v_mul_f32_e32 v17, 0x3d372713, v25
	v_mul_f32_e32 v17, v17, v25
	v_fmac_f32_e32 v27, v17, v27
	v_mul_f32_e32 v17, 0x3f4c422a, v27
	v_mul_f32_e32 v17, -2.0, v17
	v_mul_f32_e32 v17, 0x3fb8aa3b, v17
	v_exp_f32_e32 v17, v17
	v_and_b32_e32 v21, 0xffff0000, v21
	v_add_f32_e32 v17, 1.0, v17
	v_rcp_f32_e32 v27, v17
	s_waitcnt vmcnt(0)
; __device__ __forceinline__ unsigned pk2(float lo, float hi) { const f32x2v v = {lo, hi}; const bf16x2v r = __builtin_convertvector(v, bf16x2v); return __builtin_bit_cast(unsigned, r); }
; __device__ __forceinline__ float gelu_t(float x) { float u = 0.7978845608028654f * (x + 0.044715f * x * x * x); return x * __builtin_amdgcn_rcpf(1.f + __expf(-2.f * u)); }
; __device__ __forceinline__ void mixA_item(const Params& P, int layer, int idx, const bf16_t* z, bf16_t* y, char* lds) {
;     ...
;   for (int tm = 0; tm < 2; ++tm) {
;     const int t = 32 * w + tm * 16 + fr;
;     const float bias = P.sgu_b[(layer * 4 + g) * 128 + t];
; #pragma unroll
;     for (int dn = 0; dn < 4; ++dn) {
;       const int d = dn * 16 + 4 * fq;
;       const uint2 uu = *(const uint2*)(z + (size_t)(tok0 + t) * LDZ + ZC_AU + g * 64 + d);
;       const float u0 = gelu_t(__uint_as_float(uu.x << 16)), u1 = gelu_t(__uint_as_float(uu.x & 0xffff0000u)),
;                   u2 = gelu_t(__uint_as_float(uu.y << 16)), u3 = gelu_t(__uint_as_float(uu.y & 0xffff0000u));
;       uint2 o; o.x = pk2(u0 * (acc[tm][dn][0] + bias), u1 * (acc[tm][dn][1] + bias)); o.y = pk2(u2 * (acc[tm][dn][2] + bias), u3 * (acc[tm][dn][3] + bias));
;       *(uint2*)(y + (size_t)(tok0 + t) * 1024 + g * 64 + d) = o;
;     }
;   }
;   __syncthreads();
	v_pk_add_f32 v[12:13], v[12:13], v[16:17] op_sel_hi:[1,0]
	v_mov_b32_e32 v17, v21
	v_pk_mul_f32 v[24:25], v[26:27], v[24:25]
	s_nop 0
	v_pk_mul_f32 v[12:13], v[12:13], v[24:25]
	s_nop 0
	v_cvt_pk_bf16_f32 v24, v12, v13
	v_mul_f32_e32 v12, 0x3d372713, v20
	v_mul_f32_e32 v12, v12, v20
	v_mov_b32_e32 v13, v20
	v_fmac_f32_e32 v13, v12, v13
	v_mul_f32_e32 v12, 0x3f4c422a, v13
	v_mul_f32_e32 v13, 0x3d372713, v21
	v_mul_f32_e32 v13, v13, v21
	v_fmac_f32_e32 v17, v13, v17
	v_mul_f32_e32 v13, 0x3f4c422a, v17
	v_mul_f32_e32 v12, -2.0, v12
	v_mul_f32_e32 v13, -2.0, v13
	v_mul_f32_e32 v12, 0x3fb8aa3b, v12
	v_mul_f32_e32 v13, 0x3fb8aa3b, v13
	v_exp_f32_e32 v12, v12
	v_exp_f32_e32 v13, v13
	v_pk_add_f32 v[14:15], v[14:15], v[16:17] op_sel_hi:[1,0]
	v_add_f32_e32 v12, 1.0, v12
	v_add_f32_e32 v13, 1.0, v13
	v_rcp_f32_e32 v12, v12
	v_rcp_f32_e32 v13, v13
	s_nop 0
	v_pk_mul_f32 v[12:13], v[12:13], v[20:21]
	s_nop 0
	v_pk_mul_f32 v[12:13], v[14:15], v[12:13]
	v_mov_b32_e32 v14, v96
	v_mov_b32_e32 v15, v97
	v_cvt_pk_bf16_f32 v25, v12, v13
	v_lshl_add_u64 v[12:13], v[22:23], 0, v[176:177]
	global_store_dwordx2 v[12:13], v[24:25], off
	v_lshlrev_b32_e32 v20, 16, v14
	v_mul_f32_e32 v17, 0x3d372713, v20
	v_mul_f32_e32 v17, v17, v20
	v_mov_b32_e32 v22, v20
	v_fmac_f32_e32 v22, v17, v22
	v_mul_f32_e32 v17, 0x3f4c422a, v22
	v_mul_f32_e32 v17, -2.0, v17
	v_mul_f32_e32 v17, 0x3fb8aa3b, v17
	v_exp_f32_e32 v17, v17
	v_and_b32_e32 v21, 0xffff0000, v14
	v_mov_b32_e32 v23, v21
	v_lshlrev_b32_e32 v14, 16, v15
	v_add_f32_e32 v17, 1.0, v17
	v_rcp_f32_e32 v22, v17
	v_mul_f32_e32 v17, 0x3d372713, v21
	v_mul_f32_e32 v17, v17, v21
	v_fmac_f32_e32 v23, v17, v23
	v_mul_f32_e32 v17, 0x3f4c422a, v23
	v_mul_f32_e32 v17, -2.0, v17
	v_mul_f32_e32 v17, 0x3fb8aa3b, v17
	v_exp_f32_e32 v17, v17
	v_and_b32_e32 v15, 0xffff0000, v15
	v_add_f32_e32 v17, 1.0, v17
	v_rcp_f32_e32 v23, v17
	v_pk_add_f32 v[8:9], v[8:9], v[16:17] op_sel_hi:[1,0]
	v_mov_b32_e32 v17, v14
	v_pk_mul_f32 v[20:21], v[22:23], v[20:21]
	s_nop 0
	v_pk_mul_f32 v[8:9], v[8:9], v[20:21]
	s_nop 0
	v_cvt_pk_bf16_f32 v8, v8, v9
	v_mul_f32_e32 v9, 0x3d372713, v14
	v_mul_f32_e32 v9, v9, v14
	v_fmac_f32_e32 v17, v9, v17
	v_mul_f32_e32 v9, 0x3f4c422a, v17
	v_mul_f32_e32 v9, -2.0, v9
	v_mul_f32_e32 v9, 0x3fb8aa3b, v9
	v_exp_f32_e32 v9, v9
	v_mov_b32_e32 v17, v15
	v_add_f32_e32 v9, 1.0, v9
	v_rcp_f32_e32 v20, v9
	v_mul_f32_e32 v9, 0x3d372713, v15
	v_mul_f32_e32 v9, v9, v15
	v_fmac_f32_e32 v17, v9, v17
	v_mul_f32_e32 v9, 0x3f4c422a, v17
	v_mul_f32_e32 v9, -2.0, v9
	v_mul_f32_e32 v9, 0x3fb8aa3b, v9
	v_exp_f32_e32 v9, v9
	v_pk_add_f32 v[10:11], v[10:11], v[16:17] op_sel_hi:[1,0]
	v_add_f32_e32 v9, 1.0, v9
	v_rcp_f32_e32 v21, v9
	s_nop 0
	v_pk_mul_f32 v[14:15], v[20:21], v[14:15]
	s_nop 0
	v_pk_mul_f32 v[10:11], v[10:11], v[14:15]
	s_nop 0
	v_cvt_pk_bf16_f32 v9, v10, v11
	global_store_dwordx2 v[12:13], v[8:9], off offset:32
	v_mov_b32_e32 v8, v98
	v_mov_b32_e32 v9, v99
	v_lshlrev_b32_e32 v10, 16, v8
	v_mul_f32_e32 v14, 0x3d372713, v10
	v_mul_f32_e32 v14, v14, v10
	v_mov_b32_e32 v15, v10
	v_and_b32_e32 v11, 0xffff0000, v8
	v_fmac_f32_e32 v15, v14, v15
	v_mul_f32_e32 v14, 0x3f4c422a, v15
	v_mul_f32_e32 v15, 0x3d372713, v11
	v_mul_f32_e32 v15, v15, v11
	v_mov_b32_e32 v17, v11
	v_fmac_f32_e32 v17, v15, v17
	v_mul_f32_e32 v15, 0x3f4c422a, v17
	v_mul_f32_e32 v14, -2.0, v14
	v_mul_f32_e32 v15, -2.0, v15
	v_mul_f32_e32 v14, 0x3fb8aa3b, v14
	v_mul_f32_e32 v15, 0x3fb8aa3b, v15
	v_exp_f32_e32 v14, v14
	v_exp_f32_e32 v15, v15
	v_pk_add_f32 v[4:5], v[4:5], v[16:17] op_sel_hi:[1,0]
	v_lshlrev_b32_e32 v8, 16, v9
	v_add_f32_e32 v14, 1.0, v14
	v_add_f32_e32 v15, 1.0, v15
	v_rcp_f32_e32 v14, v14
	v_rcp_f32_e32 v15, v15
	v_and_b32_e32 v9, 0xffff0000, v9
	v_pk_add_f32 v[6:7], v[6:7], v[16:17] op_sel_hi:[1,0]
	v_pk_add_f32 v[0:1], v[0:1], v[16:17] op_sel_hi:[1,0]
	v_pk_mul_f32 v[10:11], v[14:15], v[10:11]
	v_pk_add_f32 v[2:3], v[2:3], v[16:17] op_sel_hi:[1,0]
	v_pk_mul_f32 v[4:5], v[4:5], v[10:11]
	v_mov_b32_e32 v10, v8
	v_cvt_pk_bf16_f32 v4, v4, v5
	v_mul_f32_e32 v5, 0x3d372713, v8
	v_mul_f32_e32 v5, v5, v8
	v_fmac_f32_e32 v10, v5, v10
	v_mul_f32_e32 v5, 0x3f4c422a, v10
	v_mul_f32_e32 v5, -2.0, v5
	v_mul_f32_e32 v5, 0x3fb8aa3b, v5
	v_exp_f32_e32 v5, v5
	v_mov_b32_e32 v11, v9
	v_add_f32_e32 v5, 1.0, v5
	v_rcp_f32_e32 v10, v5
	v_mul_f32_e32 v5, 0x3d372713, v9
	v_mul_f32_e32 v5, v5, v9
	v_fmac_f32_e32 v11, v5, v11
	v_mul_f32_e32 v5, 0x3f4c422a, v11
	v_mul_f32_e32 v5, -2.0, v5
	v_mul_f32_e32 v5, 0x3fb8aa3b, v5
	v_exp_f32_e32 v5, v5
	s_nop 0
	v_add_f32_e32 v5, 1.0, v5
	v_rcp_f32_e32 v11, v5
	s_nop 0
	v_pk_mul_f32 v[8:9], v[10:11], v[8:9]
	s_nop 0
	v_pk_mul_f32 v[6:7], v[6:7], v[8:9]
	s_nop 0
	v_cvt_pk_bf16_f32 v5, v6, v7
	global_store_dwordx2 v[12:13], v[4:5], off offset:64
	v_mov_b32_e32 v4, v100
	v_mov_b32_e32 v5, v101
	v_lshlrev_b32_e32 v6, 16, v4
	v_mul_f32_e32 v8, 0x3d372713, v6
	v_mul_f32_e32 v8, v8, v6
	v_mov_b32_e32 v9, v6
	v_and_b32_e32 v7, 0xffff0000, v4
	v_fmac_f32_e32 v9, v8, v9
	v_mul_f32_e32 v8, 0x3f4c422a, v9
	v_mul_f32_e32 v9, 0x3d372713, v7
	v_mul_f32_e32 v9, v9, v7
	v_mov_b32_e32 v10, v7
	v_fmac_f32_e32 v10, v9, v10
	v_mul_f32_e32 v9, 0x3f4c422a, v10
	v_mul_f32_e32 v8, -2.0, v8
	v_mul_f32_e32 v9, -2.0, v9
	v_mul_f32_e32 v8, 0x3fb8aa3b, v8
	v_mul_f32_e32 v9, 0x3fb8aa3b, v9
	v_exp_f32_e32 v8, v8
	v_exp_f32_e32 v9, v9
	v_lshlrev_b32_e32 v4, 16, v5
	v_and_b32_e32 v5, 0xffff0000, v5
	v_add_f32_e32 v8, 1.0, v8
	v_add_f32_e32 v9, 1.0, v9
	v_rcp_f32_e32 v8, v8
	v_rcp_f32_e32 v9, v9
	s_nop 0
	v_pk_mul_f32 v[6:7], v[8:9], v[6:7]
	s_nop 0
	v_pk_mul_f32 v[0:1], v[0:1], v[6:7]
	v_mov_b32_e32 v6, v4
	v_cvt_pk_bf16_f32 v0, v0, v1
	v_mul_f32_e32 v1, 0x3d372713, v4
	v_mul_f32_e32 v1, v1, v4
	v_fmac_f32_e32 v6, v1, v6
	v_mul_f32_e32 v1, 0x3f4c422a, v6
	v_mul_f32_e32 v1, -2.0, v1
	v_mul_f32_e32 v1, 0x3fb8aa3b, v1
	v_exp_f32_e32 v1, v1
	v_mov_b32_e32 v7, v5
	v_add_f32_e32 v1, 1.0, v1
	v_rcp_f32_e32 v6, v1
	v_mul_f32_e32 v1, 0x3d372713, v5
	v_mul_f32_e32 v1, v1, v5
	v_fmac_f32_e32 v7, v1, v7
	v_mul_f32_e32 v1, 0x3f4c422a, v7
	v_mul_f32_e32 v1, -2.0, v1
	v_mul_f32_e32 v1, 0x3fb8aa3b, v1
	v_exp_f32_e32 v1, v1
	s_nop 0
	v_add_f32_e32 v1, 1.0, v1
	v_rcp_f32_e32 v7, v1
	s_nop 0
	v_pk_mul_f32 v[4:5], v[6:7], v[4:5]
	s_nop 0
	v_pk_mul_f32 v[2:3], v[2:3], v[4:5]
	s_nop 0
	v_cvt_pk_bf16_f32 v1, v2, v3
	global_store_dwordx2 v[12:13], v[0:1], off offset:96
	s_barrier
	s_andn2_b64 exec, exec, s[36:37]
	s_cbranch_execnz .LBB0_548

; __device__ __forceinline__ bf16_t f2bf(float f) { unsigned u = __float_as_uint(f); u += 0x7fffu + ((u >> 16) & 1u); return (bf16_t)(u >> 16); }
; __device__ __forceinline__ void mixB1_item(const Params& P, int layer, int idx, const bf16_t* z, float* hsl, float* Pc, float* carryP, float* carryH, char* lds) {
;     ...
; #pragma unroll
;     for (int k = 0; k < 4; ++k) {
;       const int pos = c * 64 + t - 3 + k;
;       if (pos >= 0) {
;         const bf16_t* zr = z + (tokb + pos) * LDZ + ZC_BX + g * 64 + q * 16;
;         float v[16]; unpack8(*(const u32x4*)zr, v); unpack8(*(const u32x4*)(zr + 8), v + 8);
;         const float* cw = P.conv_w + (size_t)(layer * 4 + k) * 256 + g * 64 + q * 16;
; #pragma unroll
;         for (int i = 0; i < 16; ++i) accv[i] += v[i] * cw[i];
;       }
;     }
; #pragma unroll
;     for (int i = 0; i < 16; ++i) { xcf[t * 65 + q * 16 + i] = accv[i]; xcb[t * 72 + q * 16 + i] = f2bf(accv[i]); }
;   }
;   __syncthreads();
.LBB0_562:
	s_or_b64 exec, exec, s[0:1]
	v_or3_b32 v17, v24, v37, v32
	v_mov_b64_e32 v[20:21], s[84:85]
	v_mad_u64_u32 v[20:21], s[0:1], v17, s39, v[20:21]
	v_mad_i32_i24 v21, v33, s39, v21
	v_mov_b32_e32 v19, v177
	v_lshl_add_u64 v[18:19], v[20:21], 0, v[18:19]
	v_mov_b32_e32 v17, v177
	v_lshl_add_u64 v[18:19], v[18:19], 0, v[16:17]
	v_mul_u32_u24_e32 v17, 0x104, v24
	global_load_dwordx4 v[20:23], v[18:19], off offset:1040
	global_load_dwordx4 v[44:47], v[18:19], off offset:1024
	v_add3_u32 v56, v60, v17, v176
	v_mul_u32_u24_e32 v17, 0x90, v24
	v_add3_u32 v41, v60, v17, v16
	global_load_dwordx4 v[16:19], v[28:29], off offset:3120
	global_load_dwordx4 v[24:27], v[28:29], off offset:3104
	global_load_dwordx4 v[48:51], v[28:29], off offset:3088
	global_load_dwordx4 v[52:55], v[28:29], off offset:3072
	v_add_u32_e32 v57, 0x2400, v56
	s_mov_b32 s0, 0x7060302
	v_and_b32_e32 v40, 0xff, v43
	v_lshrrev_b32_e32 v39, 6, v40
	v_and_b32_e32 v31, 15, v43
	v_lshl_or_b32 v176, v30, 13, s17
	v_mov_b32_e32 v69, v177
	v_and_b32_e32 v38, 63, v43
	v_readlane_b32 s64, v252, 2
	v_readlane_b32 s65, v252, 3
	v_readlane_b32 s66, v252, 4
	v_readlane_b32 s67, v252, 5
	v_readlane_b32 s68, v252, 6
	v_readlane_b32 s69, v252, 7
	v_readlane_b32 s70, v252, 8
	v_readlane_b32 s71, v252, 9
	v_readlane_b32 s72, v252, 10
	v_readlane_b32 s73, v252, 11
	v_readlane_b32 s74, v252, 12
	v_readlane_b32 s75, v252, 13
	v_readlane_b32 s60, v252, 18
	v_readlane_b32 s78, v252, 16
	v_readlane_b32 s79, v252, 17
	v_readlane_b32 s62, v252, 20
	v_readlane_b32 s63, v252, 21
	v_readlane_b32 s64, v252, 22
	v_readlane_b32 s65, v252, 23
	s_mov_b32 s30, 0xbeaaaaab
	s_mov_b32 s31, 0xf800000
	v_readlane_b32 s76, v252, 14
	v_readlane_b32 s77, v252, 15
	v_readlane_b32 s61, v252, 19
	v_readlane_b32 s66, v252, 24
	v_readlane_b32 s67, v252, 25
	v_readlane_b32 s68, v252, 26
	v_readlane_b32 s69, v252, 27
	v_readlane_b32 s70, v252, 28
	v_readlane_b32 s71, v252, 29
	v_readlane_b32 s72, v252, 30
	v_readlane_b32 s73, v252, 31
	v_readlane_b32 s74, v252, 32
	v_readlane_b32 s75, v252, 33
	s_waitcnt vmcnt(0)
	v_lshlrev_b32_e32 v28, 16, v44
	v_and_b32_e32 v29, 0xffff0000, v44
	v_add_u32_e32 v44, 0x2408, v56
	v_pk_fma_f32 v[12:13], v[52:53], v[28:29], v[12:13]
	v_lshlrev_b32_e32 v28, 16, v45
	v_and_b32_e32 v29, 0xffff0000, v45
	v_pk_fma_f32 v[14:15], v[54:55], v[28:29], v[14:15]
	ds_write2_b32 v44, v14, v15 offset1:1
	v_bfe_u32 v28, v15, 16, 1
	v_bfe_u32 v29, v14, 16, 1
	v_bfe_u32 v44, v13, 16, 1
	v_bfe_u32 v45, v12, 16, 1
	ds_write2_b32 v57, v12, v13 offset1:1
	v_add3_u32 v14, v14, v29, s38
	v_add3_u32 v15, v15, v28, s38
	v_add3_u32 v28, v12, v45, s38
	v_add3_u32 v29, v13, v44, s38
	v_lshlrev_b32_e32 v12, 16, v46
	v_and_b32_e32 v13, 0xffff0000, v46
	v_add_u32_e32 v44, 0x2410, v56
	v_pk_fma_f32 v[8:9], v[48:49], v[12:13], v[8:9]
	v_lshlrev_b32_e32 v12, 16, v47
	v_and_b32_e32 v13, 0xffff0000, v47
	ds_write2_b32 v44, v8, v9 offset1:1
	v_add_u32_e32 v44, 0x2418, v56
	v_pk_fma_f32 v[10:11], v[50:51], v[12:13], v[10:11]
	ds_write2_b32 v44, v10, v11 offset1:1
	v_bfe_u32 v12, v11, 16, 1
	v_bfe_u32 v13, v10, 16, 1
	v_bfe_u32 v44, v9, 16, 1
	v_bfe_u32 v45, v8, 16, 1
	v_add3_u32 v10, v10, v13, s38
	v_add3_u32 v11, v11, v12, s38
	v_add3_u32 v8, v8, v45, s38
	v_add3_u32 v12, v9, v44, s38
	v_perm_b32 v11, v11, v10, s0
	v_perm_b32 v9, v15, v14, s0
	v_perm_b32 v10, v12, v8, s0
	v_perm_b32 v8, v29, v28, s0
	ds_write_b128 v41, v[8:11]
	v_lshlrev_b32_e32 v8, 16, v20
	v_and_b32_e32 v9, 0xffff0000, v20
	v_add_u32_e32 v10, 0x2420, v56
	v_pk_fma_f32 v[4:5], v[24:25], v[8:9], v[4:5]
	v_lshlrev_b32_e32 v8, 16, v21
	v_and_b32_e32 v9, 0xffff0000, v21
	ds_write2_b32 v10, v4, v5 offset1:1
	v_add_u32_e32 v10, 0x2428, v56
	v_pk_fma_f32 v[6:7], v[26:27], v[8:9], v[6:7]
	ds_write2_b32 v10, v6, v7 offset1:1
	v_bfe_u32 v8, v7, 16, 1
	v_bfe_u32 v9, v6, 16, 1
	v_bfe_u32 v10, v5, 16, 1
	v_bfe_u32 v11, v4, 16, 1
	v_add3_u32 v6, v6, v9, s38
	v_add3_u32 v7, v7, v8, s38
	v_add3_u32 v8, v4, v11, s38
	v_add3_u32 v9, v5, v10, s38
	v_lshlrev_b32_e32 v4, 16, v22
	v_and_b32_e32 v5, 0xffff0000, v22
	v_add_u32_e32 v10, 0x2430, v56
	v_pk_fma_f32 v[0:1], v[16:17], v[4:5], v[0:1]
	v_lshlrev_b32_e32 v4, 16, v23
	v_and_b32_e32 v5, 0xffff0000, v23
	ds_write2_b32 v10, v0, v1 offset1:1
	v_add_u32_e32 v10, 0x2438, v56
	v_pk_fma_f32 v[2:3], v[18:19], v[4:5], v[2:3]
	ds_write2_b32 v10, v2, v3 offset1:1
	v_bfe_u32 v4, v3, 16, 1
	v_bfe_u32 v5, v2, 16, 1
	v_bfe_u32 v10, v1, 16, 1
	v_bfe_u32 v11, v0, 16, 1
	v_add3_u32 v2, v2, v5, s38
	v_add3_u32 v3, v3, v4, s38
	v_add3_u32 v0, v0, v11, s38
	v_add3_u32 v4, v1, v10, s38
	v_perm_b32 v3, v3, v2, s0
	v_perm_b32 v1, v7, v6, s0
	v_perm_b32 v2, v4, v0, s0
	v_perm_b32 v0, v9, v8, s0
	ds_write_b128 v41, v[0:3] offset:16
	v_lshlrev_b32_e32 v41, 4, v39
	v_or_b32_e32 v72, v41, v31
	v_lshl_add_u64 v[0:1], s[88:89], 0, v[176:177]
	v_lshl_add_u64 v[2:3], s[90:91], 0, v[176:177]
	v_mul_u32_u24_e32 v4, 0x90, v72
	v_and_b32_e32 v176, 48, v43
	v_add3_u32 v30, v60, v4, v176
	v_lshl_add_u64 v[28:29], v[0:1], 0, v[176:177]
	v_lshl_add_u64 v[62:63], v[2:3], 0, v[176:177]
	v_lshlrev_b32_e32 v176, 7, v31
	v_or_b32_e32 v68, 0x1000, v176
	v_lshl_add_u64 v[64:65], v[28:29], 0, v[176:177]
	v_lshl_add_u64 v[66:67], v[62:63], 0, v[176:177]
	v_lshl_add_u64 v[20:21], v[28:29], 0, v[68:69]
	v_lshl_add_u64 v[24:25], v[62:63], 0, v[68:69]
	s_waitcnt lgkmcnt(0)
	s_barrier
; __device__ __forceinline__ float sigm(float x) { return __builtin_amdgcn_rcpf(1.f + __expf(-x)); }
; __device__ __forceinline__ f32x4 mfma16(bf16x8 a, bf16x8 b, f32x4 c) { return __builtin_amdgcn_mfma_f32_16x16x32_bf16(a, b, c, 0, 0, 0); }
; __device__ __forceinline__ void mixB1_item(const Params& P, int layer, int idx, const bf16_t* z, float* hsl, float* Pc, float* carryP, float* carryH, char* lds) {
;     ...
;   {
;     const bf16_t* wa = (const bf16_t*)(P.ws + OFF_WAT) + (layer * 4 + g) * 4096;
;     const bf16_t* wx = (const bf16_t*)(P.ws + OFF_WXT) + (layer * 4 + g) * 4096;
;     f32x4 ar[4] = {}, ai[4] = {};
; #pragma unroll
;     for (int ks = 0; ks < 2; ++ks) {
;       const bf16x8 xf = *(const bf16x8*)(xcb + (16 * w + fr) * 72 + ks * 32 + 8 * fq);
; #pragma unroll
;       for (int jn = 0; jn < 4; ++jn) {
;         const bf16x8 fa = *(const bf16x8*)(wa + (jn * 16 + fr) * 64 + ks * 32 + 8 * fq);
;         const bf16x8 fx = *(const bf16x8*)(wx + (jn * 16 + fr) * 64 + ks * 32 + 8 * fq);
;         ar[jn] = mfma16(fa, xf, ar[jn]); ai[jn] = mfma16(fx, xf, ai[jn]);
;       }
;     }
;     const int t = 16 * w + fr;
; #pragma unroll
;     for (int jn = 0; jn < 4; ++jn)
; #pragma unroll
;       for (int e = 0; e < 4; ++e) {
;         const int j = jn * 16 + 4 * fq + e, ch = layer * 256 + g * 64 + j;
;         const float r = sigm(ar[jn][e] + P.lru_ba[ch]), ig = sigm(ai[jn][e] + P.lru_bx[ch]);
;         const float lam = P.lru_lam[ch];
;         const float xe = __expf(-lam);
;         float m8; asm volatile("v_mov_b32 %0, 0xc1000000" : "=v"(m8));
;         const float la = m8 * r * (xe * (1.f - xe * (0.5f - xe * (1.f / 3.f))));
;         const float av = __expf(la);
;         const float y2 = 2.f * la;
;         const float om = -y2 * (1.f + y2 * (0.5f + y2 * ((1.f / 6.f) + y2 * ((1.f / 24.f) + y2 * ((1.f / 120.f) + y2 * (1.f / 720.f))))));
;         const float bv = sqrtf(om) * (ig * xcf[t * 65 + j]);
;         aA[t * 65 + j] = av; bB[t * 65 + j] = bv;
;       }
	v_lshrrev_b32_e32 v73, 2, v179
	v_and_b32_e32 v73, 12, v73
	v_add_lshl_u32 v80, v73, v42, 2
	global_load_dwordx4 v[84:87], v80, s[78:79]
	global_load_dwordx4 v[88:91], v80, s[78:79] offset:64
	global_load_dwordx4 v[92:95], v80, s[78:79] offset:128
	global_load_dwordx4 v[96:99], v80, s[78:79] offset:192
	global_load_dwordx4 v[100:103], v80, s[62:63]
	global_load_dwordx4 v[104:107], v80, s[62:63] offset:64
	global_load_dwordx4 v[108:111], v80, s[62:63] offset:128
	global_load_dwordx4 v[112:115], v80, s[62:63] offset:192
	global_load_dwordx4 v[116:119], v80, s[64:65]
	global_load_dwordx4 v[120:123], v80, s[64:65] offset:64
	global_load_dwordx4 v[124:127], v80, s[64:65] offset:128
	global_load_dwordx4 v[128:131], v80, s[64:65] offset:192
	ds_read_b128 v[0:3], v30
	ds_read_b128 v[56:59], v30 offset:64
	v_add_co_u32_e32 v132, vcc, 0x1000, v64
	s_nop 1
	v_addc_co_u32_e32 v133, vcc, 0, v65, vcc
	v_add_co_u32_e32 v134, vcc, 0x1000, v66
	s_nop 1
	v_addc_co_u32_e32 v135, vcc, 0, v67, vcc
	global_load_dwordx4 v[136:139], v[64:65], off
	global_load_dwordx4 v[140:143], v[132:133], off
	global_load_dwordx4 v[144:147], v[134:135], off
	global_load_dwordx4 v[148:151], v[66:67], off
	global_load_dwordx4 v[152:155], v[64:65], off offset:2048
	global_load_dwordx4 v[156:159], v[66:67], off offset:2048
	global_load_dwordx4 v[160:163], v[132:133], off offset:2048
	global_load_dwordx4 v[164:167], v[134:135], off offset:2048
	global_load_dwordx4 v[168:171], v[64:65], off offset:64
	global_load_dwordx4 v[172:175], v[66:67], off offset:64
	global_load_dwordx4 v[180:183], v[64:65], off offset:2112
	global_load_dwordx4 v[184:187], v[66:67], off offset:2112
	global_load_dwordx4 v[188:191], v[132:133], off offset:64
	global_load_dwordx4 v[192:195], v[134:135], off offset:64
	global_load_dwordx4 v[196:199], v[134:135], off offset:2112
	global_load_dwordx4 v[200:203], v[132:133], off offset:2112
	v_lshrrev_b32_e32 v43, 2, v43
	v_and_b32_e32 v43, 12, v43
	s_waitcnt vmcnt(15) lgkmcnt(1)
	v_mfma_f32_16x16x32_bf16 v[4:7], v[136:139], v[0:3], 0
	s_waitcnt vmcnt(14)
	v_mfma_f32_16x16x32_bf16 v[44:47], v[140:143], v[0:3], 0
	s_waitcnt vmcnt(13)
	v_mfma_f32_16x16x32_bf16 v[48:51], v[144:147], v[0:3], 0
	s_waitcnt vmcnt(12)
	v_mfma_f32_16x16x32_bf16 v[8:11], v[148:151], v[0:3], 0
	s_waitcnt vmcnt(11)
	v_mfma_f32_16x16x32_bf16 v[12:15], v[152:155], v[0:3], 0
	s_waitcnt vmcnt(10)
	v_mfma_f32_16x16x32_bf16 v[16:19], v[156:159], v[0:3], 0
	s_waitcnt vmcnt(9)
	v_mfma_f32_16x16x32_bf16 v[52:55], v[160:163], v[0:3], 0
	s_waitcnt vmcnt(8)
	v_mfma_f32_16x16x32_bf16 v[0:3], v[164:167], v[0:3], 0
	s_waitcnt vmcnt(7) lgkmcnt(0)
	v_mfma_f32_16x16x32_bf16 v[28:31], v[168:171], v[56:59], v[4:7]
	s_waitcnt vmcnt(6)
	v_mfma_f32_16x16x32_bf16 v[24:27], v[172:175], v[56:59], v[8:11]
	s_waitcnt vmcnt(5)
	v_mfma_f32_16x16x32_bf16 v[20:23], v[180:183], v[56:59], v[12:15]
	s_waitcnt vmcnt(4)
	v_mfma_f32_16x16x32_bf16 v[16:19], v[184:187], v[56:59], v[16:19]
	s_waitcnt vmcnt(3)
	v_mfma_f32_16x16x32_bf16 v[12:15], v[188:191], v[56:59], v[44:47]
	s_waitcnt vmcnt(2)
	v_mfma_f32_16x16x32_bf16 v[8:11], v[192:195], v[56:59], v[48:51]
	s_waitcnt vmcnt(1)
	v_mfma_f32_16x16x32_bf16 v[0:3], v[196:199], v[56:59], v[0:3]
	v_or_b32_e32 v44, v43, v42
	v_lshlrev_b32_e32 v44, 2, v44
	v_mov_b32_e32 v45, v84
	v_mov_b32_e32 v46, v100
	v_add_lshl_u32 v42, v43, v42, 2
	s_waitcnt vmcnt(0)
	v_mfma_f32_16x16x32_bf16 v[4:7], v[200:203], v[56:59], v[52:55]
	s_waitcnt vmcnt(1)
	v_add_f32_e32 v28, v28, v45
	s_waitcnt vmcnt(0)
	v_add_f32_e32 v24, v24, v46
	v_mul_f32_e32 v24, 0xbfb8aa3b, v24
	v_exp_f32_e32 v24, v24
	v_mul_f32_e32 v28, 0xbfb8aa3b, v28
	v_exp_f32_e32 v45, v28
	v_mov_b32_e32 v28, 1.0
	v_add_f32_e32 v24, 1.0, v24
	v_rcp_f32_e32 v46, v24
	v_mov_b32_e32 v24, v116
	v_add_f32_e32 v45, 1.0, v45
	v_rcp_f32_e32 v45, v45
	v_mov_b32 v44, 0xc1000000
	s_waitcnt vmcnt(0)
	v_mul_f32_e32 v24, 0xbfb8aa3b, v24
	v_exp_f32_e32 v24, v24
	v_mul_f32_e32 v44, v44, v45
	v_fma_f32 v45, v24, s30, 0.5
	v_fma_f32 v45, -v24, v45, 1.0
	v_mul_f32_e32 v24, v24, v45
	v_mul_f32_e32 v24, v44, v24
	v_mul_f32_e32 v44, 0x3fb8aa3b, v24
	v_add_f32_e32 v24, v24, v24
	v_fmamk_f32 v45, v24, 0x3ab60b61, v213
	v_fmaak_f32 v45, v24, v45, 0x3d2aaaab
	v_fmaak_f32 v45, v24, v45, 0x3e2aaaab
	v_fma_f32 v45, v24, v45, 0.5
	v_fma_f32 v45, v24, v45, 1.0
	v_mul_f32_e64 v24, v45, -v24
	v_cmp_gt_f32_e32 vcc, s31, v24
	v_mul_f32_e32 v45, 0x4f800000, v24
	v_exp_f32_e32 v44, v44
	v_cndmask_b32_e32 v24, v24, v45, vcc
	v_sqrt_f32_e32 v45, v24
	s_nop 0
	v_add_u32_e32 v47, -1, v45
	v_fma_f32 v48, -v47, v45, v24
	v_cmp_ge_f32_e64 s[0:1], 0, v48
	v_add_u32_e32 v48, 1, v45
	s_nop 0
	v_cndmask_b32_e64 v47, v45, v47, s[0:1]
	v_fma_f32 v45, -v48, v45, v24
	v_cmp_lt_f32_e64 s[0:1], 0, v45
	s_nop 1
	v_cndmask_b32_e64 v45, v47, v48, s[0:1]
	v_mul_f32_e32 v47, 0x37800000, v45
	v_cndmask_b32_e32 v45, v45, v47, vcc
	v_cmp_class_f32_e32 vcc, v24, v214
	s_nop 1
	v_cndmask_b32_e32 v45, v45, v24, vcc
	v_mad_u32_u24 v24, v72, s33, v43
	v_mov_b32_e32 v43, v85
	v_lshl_add_u32 v24, v24, 2, v60
	ds_read_b32 v47, v24 offset:9216
	s_waitcnt lgkmcnt(0)
	v_mul_f32_e32 v46, v47, v46
	v_mul_f32_e32 v45, v46, v45
	ds_write2st64_b32 v24, v44, v45 offset0:101 offset1:166
	s_waitcnt vmcnt(0)
	v_add_f32_e32 v29, v29, v43
	v_mov_b32_e32 v43, v101
	v_mul_f32_e32 v29, 0xbfb8aa3b, v29
	v_exp_f32_e32 v29, v29
	s_waitcnt vmcnt(0)
	v_add_f32_e32 v25, v25, v43
	v_mov_b32_e32 v43, v117
	v_add_f32_e32 v29, 1.0, v29
	v_rcp_f32_e32 v29, v29
	v_mov_b32 v44, 0xc1000000
	v_mul_f32_e32 v25, 0xbfb8aa3b, v25
	v_exp_f32_e32 v25, v25
	v_mul_f32_e32 v29, v44, v29
	v_add_f32_e32 v25, 1.0, v25
	v_rcp_f32_e32 v25, v25
	s_waitcnt vmcnt(0)
; __device__ __forceinline__ float sigm(float x) { return __builtin_amdgcn_rcpf(1.f + __expf(-x)); }
; __device__ __forceinline__ void mixB1_item(const Params& P, int layer, int idx, const bf16_t* z, float* hsl, float* Pc, float* carryP, float* carryH, char* lds) {
;     ...
;     const int t = 16 * w + fr;
; #pragma unroll
;     for (int jn = 0; jn < 4; ++jn)
; #pragma unroll
;       for (int e = 0; e < 4; ++e) {
;         const int j = jn * 16 + 4 * fq + e, ch = layer * 256 + g * 64 + j;
;         const float r = sigm(ar[jn][e] + P.lru_ba[ch]), ig = sigm(ai[jn][e] + P.lru_bx[ch]);
;         const float lam = P.lru_lam[ch];
;         const float xe = __expf(-lam);
;         float m8; asm volatile("v_mov_b32 %0, 0xc1000000" : "=v"(m8));
;         const float la = m8 * r * (xe * (1.f - xe * (0.5f - xe * (1.f / 3.f))));
;         const float av = __expf(la);
;         const float y2 = 2.f * la;
;         const float om = -y2 * (1.f + y2 * (0.5f + y2 * ((1.f / 6.f) + y2 * ((1.f / 24.f) + y2 * ((1.f / 120.f) + y2 * (1.f / 720.f))))));
;         const float bv = sqrtf(om) * (ig * xcf[t * 65 + j]);
;         aA[t * 65 + j] = av; bB[t * 65 + j] = bv;
;       }
	v_mul_f32_e32 v43, 0xbfb8aa3b, v43
	v_exp_f32_e32 v43, v43
	s_nop 0
	v_fma_f32 v44, v43, s30, 0.5
	v_fma_f32 v44, -v43, v44, 1.0
	v_mul_f32_e32 v43, v43, v44
	v_mul_f32_e32 v29, v29, v43
	v_mul_f32_e32 v43, 0x3fb8aa3b, v29
	v_add_f32_e32 v29, v29, v29
	v_fmamk_f32 v44, v29, 0x3ab60b61, v213
	v_fmaak_f32 v44, v29, v44, 0x3d2aaaab
	v_fmaak_f32 v44, v29, v44, 0x3e2aaaab
	v_fma_f32 v44, v29, v44, 0.5
	v_fma_f32 v44, v29, v44, 1.0
	v_mul_f32_e64 v29, v44, -v29
	v_cmp_gt_f32_e32 vcc, s31, v29
	v_mul_f32_e32 v44, 0x4f800000, v29
	v_exp_f32_e32 v43, v43
	v_cndmask_b32_e32 v29, v29, v44, vcc
	v_sqrt_f32_e32 v44, v29
	s_nop 0
	v_add_u32_e32 v45, -1, v44
	v_fma_f32 v46, -v45, v44, v29
	v_cmp_ge_f32_e64 s[0:1], 0, v46
	v_add_u32_e32 v46, 1, v44
	s_nop 0
	v_cndmask_b32_e64 v45, v44, v45, s[0:1]
	v_fma_f32 v44, -v46, v44, v29
	v_cmp_lt_f32_e64 s[0:1], 0, v44
	s_nop 1
	v_cndmask_b32_e64 v44, v45, v46, s[0:1]
	v_mul_f32_e32 v45, 0x37800000, v44
	v_cndmask_b32_e32 v44, v44, v45, vcc
	v_cmp_class_f32_e32 vcc, v29, v214
	s_nop 1
	v_cndmask_b32_e32 v29, v44, v29, vcc
	ds_read_b32 v44, v24 offset:9220
	s_waitcnt lgkmcnt(0)
	v_mul_f32_e32 v25, v44, v25
	v_mul_f32_e32 v25, v25, v29
	v_add_u32_e32 v29, 4, v24
	ds_write2st64_b32 v29, v43, v25 offset0:101 offset1:166
	v_mov_b32_e32 v25, v86
	v_mov_b32_e32 v29, v102
	s_waitcnt vmcnt(1)
	v_add_f32_e32 v25, v30, v25
	s_waitcnt vmcnt(0)
	v_add_f32_e32 v26, v26, v29
	v_mov_b32_e32 v29, v118
	v_mul_f32_e32 v25, 0xbfb8aa3b, v25
	v_exp_f32_e32 v25, v25
	v_mov_b32 v30, 0xc1000000
	v_mul_f32_e32 v26, 0xbfb8aa3b, v26
	v_exp_f32_e32 v26, v26
	v_add_f32_e32 v25, 1.0, v25
	v_rcp_f32_e32 v25, v25
	v_add_f32_e32 v26, 1.0, v26
	v_rcp_f32_e32 v26, v26
	v_mul_f32_e32 v25, v30, v25
	s_waitcnt vmcnt(0)
	v_mul_f32_e32 v29, 0xbfb8aa3b, v29
	v_exp_f32_e32 v29, v29
	s_nop 0
	v_fma_f32 v30, v29, s30, 0.5
	v_fma_f32 v30, -v29, v30, 1.0
	v_mul_f32_e32 v29, v29, v30
	v_mul_f32_e32 v25, v25, v29
	v_mul_f32_e32 v29, 0x3fb8aa3b, v25
	v_add_f32_e32 v25, v25, v25
	v_fmamk_f32 v30, v25, 0x3ab60b61, v213
	v_fmaak_f32 v30, v25, v30, 0x3d2aaaab
	v_fmaak_f32 v30, v25, v30, 0x3e2aaaab
	v_fma_f32 v30, v25, v30, 0.5
	v_fma_f32 v30, v25, v30, 1.0
	v_mul_f32_e64 v25, v30, -v25
	v_cmp_gt_f32_e32 vcc, s31, v25
	v_mul_f32_e32 v30, 0x4f800000, v25
	v_exp_f32_e32 v29, v29
	v_cndmask_b32_e32 v25, v25, v30, vcc
	v_sqrt_f32_e32 v30, v25
	s_nop 0
	v_add_u32_e32 v43, -1, v30
	v_fma_f32 v44, -v43, v30, v25
	v_cmp_ge_f32_e64 s[0:1], 0, v44
	v_add_u32_e32 v44, 1, v30
	s_nop 0
	v_cndmask_b32_e64 v43, v30, v43, s[0:1]
	v_fma_f32 v30, -v44, v30, v25
	v_cmp_lt_f32_e64 s[0:1], 0, v30
	s_nop 1
	v_cndmask_b32_e64 v30, v43, v44, s[0:1]
	v_mul_f32_e32 v43, 0x37800000, v30
	v_cndmask_b32_e32 v30, v30, v43, vcc
	v_cmp_class_f32_e32 vcc, v25, v214
	s_nop 1
	v_cndmask_b32_e32 v25, v30, v25, vcc
	ds_read_b32 v30, v24 offset:9224
	s_waitcnt lgkmcnt(0)
	v_mul_f32_e32 v26, v30, v26
	v_mul_f32_e32 v25, v26, v25
	v_add_u32_e32 v26, 8, v24
	ds_write2st64_b32 v26, v29, v25 offset0:101 offset1:166
	v_mov_b32_e32 v25, v87
	v_mov_b32_e32 v26, v103
	s_waitcnt vmcnt(1)
	v_add_f32_e32 v25, v31, v25
	s_waitcnt vmcnt(0)
	v_add_f32_e32 v26, v27, v26
	v_mov_b32_e32 v27, v119
	v_mul_f32_e32 v25, 0xbfb8aa3b, v25
	v_exp_f32_e32 v25, v25
	v_mov_b32 v29, 0xc1000000
	v_mul_f32_e32 v26, 0xbfb8aa3b, v26
	v_exp_f32_e32 v26, v26
	v_add_f32_e32 v25, 1.0, v25
	v_rcp_f32_e32 v25, v25
	v_add_f32_e32 v26, 1.0, v26
	v_rcp_f32_e32 v26, v26
	v_mul_f32_e32 v25, v29, v25
	s_waitcnt vmcnt(0)
	v_mul_f32_e32 v27, 0xbfb8aa3b, v27
	v_exp_f32_e32 v27, v27
	s_nop 0
	v_fma_f32 v29, v27, s30, 0.5
	v_fma_f32 v29, -v27, v29, 1.0
	v_mul_f32_e32 v27, v27, v29
	v_mul_f32_e32 v25, v25, v27
	v_mul_f32_e32 v27, 0x3fb8aa3b, v25
	v_add_f32_e32 v25, v25, v25
	v_fmamk_f32 v29, v25, 0x3ab60b61, v213
	v_fmaak_f32 v29, v25, v29, 0x3d2aaaab
	v_fmaak_f32 v29, v25, v29, 0x3e2aaaab
	v_fma_f32 v29, v25, v29, 0.5
	v_fma_f32 v29, v25, v29, 1.0
	v_mul_f32_e64 v25, v29, -v25
	v_cmp_gt_f32_e32 vcc, s31, v25
	v_mul_f32_e32 v29, 0x4f800000, v25
	v_exp_f32_e32 v27, v27
	v_cndmask_b32_e32 v25, v25, v29, vcc
	v_sqrt_f32_e32 v29, v25
	s_nop 0
	v_add_u32_e32 v30, -1, v29
	v_fma_f32 v31, -v30, v29, v25
	v_cmp_ge_f32_e64 s[0:1], 0, v31
	v_add_u32_e32 v31, 1, v29
	s_nop 0
	v_cndmask_b32_e64 v30, v29, v30, s[0:1]
	v_fma_f32 v29, -v31, v29, v25
	v_cmp_lt_f32_e64 s[0:1], 0, v29
	s_nop 1
	v_cndmask_b32_e64 v29, v30, v31, s[0:1]
	v_mul_f32_e32 v30, 0x37800000, v29
	v_cndmask_b32_e32 v29, v29, v30, vcc
	v_cmp_class_f32_e32 vcc, v25, v214
	s_nop 1
	v_cndmask_b32_e32 v25, v29, v25, vcc
	ds_read_b32 v29, v24 offset:9228
	s_waitcnt lgkmcnt(0)
	v_mul_f32_e32 v26, v29, v26
	v_mul_f32_e32 v25, v26, v25
	v_add_u32_e32 v26, 12, v24
	ds_write2st64_b32 v26, v27, v25 offset0:101 offset1:166
	v_mov_b32_e32 v25, v88
	s_waitcnt vmcnt(0)
	v_add_f32_e32 v20, v20, v25
	v_mov_b32_e32 v25, v104
	v_mul_f32_e32 v20, 0xbfb8aa3b, v20
	v_exp_f32_e32 v20, v20
	s_waitcnt vmcnt(0)
	v_add_f32_e32 v16, v16, v25
	v_mov_b32_e32 v25, v120
	v_add_f32_e32 v20, 1.0, v20
	v_rcp_f32_e32 v20, v20
	v_mov_b32 v26, 0xc1000000
	v_mul_f32_e32 v16, 0xbfb8aa3b, v16
	v_exp_f32_e32 v16, v16
	v_mul_f32_e32 v20, v26, v20
	v_add_f32_e32 v16, 1.0, v16
	v_rcp_f32_e32 v16, v16
	s_waitcnt vmcnt(0)
; __device__ __forceinline__ float sigm(float x) { return __builtin_amdgcn_rcpf(1.f + __expf(-x)); }
; __device__ __forceinline__ void mixB1_item(const Params& P, int layer, int idx, const bf16_t* z, float* hsl, float* Pc, float* carryP, float* carryH, char* lds) {
;     ...
;     const int t = 16 * w + fr;
; #pragma unroll
;     for (int jn = 0; jn < 4; ++jn)
; #pragma unroll
;       for (int e = 0; e < 4; ++e) {
;         const int j = jn * 16 + 4 * fq + e, ch = layer * 256 + g * 64 + j;
;         const float r = sigm(ar[jn][e] + P.lru_ba[ch]), ig = sigm(ai[jn][e] + P.lru_bx[ch]);
;         const float lam = P.lru_lam[ch];
;         const float xe = __expf(-lam);
;         float m8; asm volatile("v_mov_b32 %0, 0xc1000000" : "=v"(m8));
;         const float la = m8 * r * (xe * (1.f - xe * (0.5f - xe * (1.f / 3.f))));
;         const float av = __expf(la);
;         const float y2 = 2.f * la;
;         const float om = -y2 * (1.f + y2 * (0.5f + y2 * ((1.f / 6.f) + y2 * ((1.f / 24.f) + y2 * ((1.f / 120.f) + y2 * (1.f / 720.f))))));
;         const float bv = sqrtf(om) * (ig * xcf[t * 65 + j]);
;         aA[t * 65 + j] = av; bB[t * 65 + j] = bv;
;       }
	v_mul_f32_e32 v25, 0xbfb8aa3b, v25
	v_exp_f32_e32 v25, v25
	s_nop 0
	v_fma_f32 v26, v25, s30, 0.5
	v_fma_f32 v26, -v25, v26, 1.0
	v_mul_f32_e32 v25, v25, v26
	v_mul_f32_e32 v20, v20, v25
	v_mul_f32_e32 v25, 0x3fb8aa3b, v20
	v_add_f32_e32 v20, v20, v20
	v_fmamk_f32 v26, v20, 0x3ab60b61, v213
	v_fmaak_f32 v26, v20, v26, 0x3d2aaaab
	v_fmaak_f32 v26, v20, v26, 0x3e2aaaab
	v_fma_f32 v26, v20, v26, 0.5
	v_fma_f32 v26, v20, v26, 1.0
	v_mul_f32_e64 v20, v26, -v20
	v_cmp_gt_f32_e32 vcc, s31, v20
	v_mul_f32_e32 v26, 0x4f800000, v20
	v_exp_f32_e32 v25, v25
	v_cndmask_b32_e32 v20, v20, v26, vcc
	v_sqrt_f32_e32 v26, v20
	s_nop 0
	v_add_u32_e32 v27, -1, v26
	v_fma_f32 v29, -v27, v26, v20
	v_cmp_ge_f32_e64 s[0:1], 0, v29
	v_add_u32_e32 v29, 1, v26
	s_nop 0
	v_cndmask_b32_e64 v27, v26, v27, s[0:1]
	v_fma_f32 v26, -v29, v26, v20
	v_cmp_lt_f32_e64 s[0:1], 0, v26
	s_nop 1
	v_cndmask_b32_e64 v26, v27, v29, s[0:1]
	v_mul_f32_e32 v27, 0x37800000, v26
	v_cndmask_b32_e32 v26, v26, v27, vcc
	v_cmp_class_f32_e32 vcc, v20, v214
	s_nop 1
	v_cndmask_b32_e32 v20, v26, v20, vcc
	ds_read_b32 v26, v24 offset:9280
	s_waitcnt lgkmcnt(0)
	v_mul_f32_e32 v16, v26, v16
	v_mul_f32_e32 v16, v16, v20
	v_add_u32_e32 v20, 64, v24
	ds_write2st64_b32 v20, v25, v16 offset0:101 offset1:166
	v_mov_b32_e32 v16, v89
	v_mov_b32_e32 v20, v105
	s_waitcnt vmcnt(1)
	v_add_f32_e32 v16, v21, v16
	s_waitcnt vmcnt(0)
	v_add_f32_e32 v17, v17, v20
	v_mov_b32_e32 v20, v121
	v_mul_f32_e32 v16, 0xbfb8aa3b, v16
	v_exp_f32_e32 v16, v16
	v_mov_b32 v21, 0xc1000000
	v_mul_f32_e32 v17, 0xbfb8aa3b, v17
	v_exp_f32_e32 v17, v17
	v_add_f32_e32 v16, 1.0, v16
	v_rcp_f32_e32 v16, v16
	v_add_f32_e32 v17, 1.0, v17
	v_rcp_f32_e32 v17, v17
	v_mul_f32_e32 v16, v21, v16
	s_waitcnt vmcnt(0)
	v_mul_f32_e32 v20, 0xbfb8aa3b, v20
	v_exp_f32_e32 v20, v20
	s_nop 0
	v_fma_f32 v21, v20, s30, 0.5
	v_fma_f32 v21, -v20, v21, 1.0
	v_mul_f32_e32 v20, v20, v21
	v_mul_f32_e32 v16, v16, v20
	v_mul_f32_e32 v20, 0x3fb8aa3b, v16
	v_add_f32_e32 v16, v16, v16
	v_fmamk_f32 v21, v16, 0x3ab60b61, v213
	v_fmaak_f32 v21, v16, v21, 0x3d2aaaab
	v_fmaak_f32 v21, v16, v21, 0x3e2aaaab
	v_fma_f32 v21, v16, v21, 0.5
	v_fma_f32 v21, v16, v21, 1.0
	v_mul_f32_e64 v16, v21, -v16
	v_cmp_gt_f32_e32 vcc, s31, v16
	v_mul_f32_e32 v21, 0x4f800000, v16
	v_exp_f32_e32 v20, v20
	v_cndmask_b32_e32 v16, v16, v21, vcc
	v_sqrt_f32_e32 v21, v16
	s_nop 0
	v_add_u32_e32 v25, -1, v21
	v_fma_f32 v26, -v25, v21, v16
	v_cmp_ge_f32_e64 s[0:1], 0, v26
	v_add_u32_e32 v26, 1, v21
	s_nop 0
	v_cndmask_b32_e64 v25, v21, v25, s[0:1]
	v_fma_f32 v21, -v26, v21, v16
	v_cmp_lt_f32_e64 s[0:1], 0, v21
	s_nop 1
	v_cndmask_b32_e64 v21, v25, v26, s[0:1]
	v_mul_f32_e32 v25, 0x37800000, v21
	v_cndmask_b32_e32 v21, v21, v25, vcc
	v_cmp_class_f32_e32 vcc, v16, v214
	s_nop 1
	v_cndmask_b32_e32 v16, v21, v16, vcc
	ds_read_b32 v21, v24 offset:9284
	s_waitcnt lgkmcnt(0)
	v_mul_f32_e32 v17, v21, v17
	v_mul_f32_e32 v16, v17, v16
	v_add_u32_e32 v17, 0x44, v24
	ds_write2st64_b32 v17, v20, v16 offset0:101 offset1:166
	v_mov_b32_e32 v16, v90
	v_mov_b32_e32 v17, v106
	s_waitcnt vmcnt(1)
	v_add_f32_e32 v16, v22, v16
	s_waitcnt vmcnt(0)
	v_add_f32_e32 v17, v18, v17
	v_mov_b32_e32 v18, v122
	v_mul_f32_e32 v16, 0xbfb8aa3b, v16
	v_exp_f32_e32 v16, v16
	v_mov_b32 v20, 0xc1000000
	v_mul_f32_e32 v17, 0xbfb8aa3b, v17
	v_exp_f32_e32 v17, v17
	v_add_f32_e32 v16, 1.0, v16
	v_rcp_f32_e32 v16, v16
	v_add_f32_e32 v17, 1.0, v17
	v_rcp_f32_e32 v17, v17
	v_mul_f32_e32 v16, v20, v16
	s_waitcnt vmcnt(0)
	v_mul_f32_e32 v18, 0xbfb8aa3b, v18
	v_exp_f32_e32 v18, v18
	s_nop 0
	v_fma_f32 v20, v18, s30, 0.5
	v_fma_f32 v20, -v18, v20, 1.0
	v_mul_f32_e32 v18, v18, v20
	v_mul_f32_e32 v16, v16, v18
	v_mul_f32_e32 v18, 0x3fb8aa3b, v16
	v_add_f32_e32 v16, v16, v16
	v_fmamk_f32 v20, v16, 0x3ab60b61, v213
	v_fmaak_f32 v20, v16, v20, 0x3d2aaaab
	v_fmaak_f32 v20, v16, v20, 0x3e2aaaab
	v_fma_f32 v20, v16, v20, 0.5
	v_fma_f32 v20, v16, v20, 1.0
	v_mul_f32_e64 v16, v20, -v16
	v_cmp_gt_f32_e32 vcc, s31, v16
	v_mul_f32_e32 v20, 0x4f800000, v16
	v_exp_f32_e32 v18, v18
	v_cndmask_b32_e32 v16, v16, v20, vcc
	v_sqrt_f32_e32 v20, v16
	s_nop 0
	v_add_u32_e32 v21, -1, v20
	v_fma_f32 v22, -v21, v20, v16
	v_cmp_ge_f32_e64 s[0:1], 0, v22
	v_add_u32_e32 v22, 1, v20
	s_nop 0
	v_cndmask_b32_e64 v21, v20, v21, s[0:1]
	v_fma_f32 v20, -v22, v20, v16
	v_cmp_lt_f32_e64 s[0:1], 0, v20
	s_nop 1
	v_cndmask_b32_e64 v20, v21, v22, s[0:1]
	v_mul_f32_e32 v21, 0x37800000, v20
	v_cndmask_b32_e32 v20, v20, v21, vcc
	v_cmp_class_f32_e32 vcc, v16, v214
	s_nop 1
	v_cndmask_b32_e32 v16, v20, v16, vcc
	ds_read_b32 v20, v24 offset:9288
	s_waitcnt lgkmcnt(0)
	v_mul_f32_e32 v17, v20, v17
	v_mul_f32_e32 v16, v17, v16
	v_add_u32_e32 v17, 0x48, v24
	ds_write2st64_b32 v17, v18, v16 offset0:101 offset1:166
	v_mov_b32_e32 v16, v91
	v_mov_b32_e32 v17, v107
	v_mov_b32_e32 v18, v123
	s_waitcnt vmcnt(2)
	v_add_f32_e32 v16, v23, v16
	v_mul_f32_e32 v16, 0xbfb8aa3b, v16
	v_exp_f32_e32 v16, v16
	s_waitcnt vmcnt(0)
	v_mul_f32_e32 v18, 0xbfb8aa3b, v18
	v_exp_f32_e32 v18, v18
	v_add_f32_e32 v17, v19, v17
	v_add_f32_e32 v16, 1.0, v16
	v_rcp_f32_e32 v16, v16
	v_mov_b32 v19, 0xc1000000
	v_mul_f32_e32 v17, 0xbfb8aa3b, v17
	v_exp_f32_e32 v17, v17
	v_mul_f32_e32 v16, v19, v16
	v_fma_f32 v19, v18, s30, 0.5
	v_fma_f32 v19, -v18, v19, 1.0
	v_mul_f32_e32 v18, v18, v19
	v_mul_f32_e32 v16, v16, v18
	v_mul_f32_e32 v18, 0x3fb8aa3b, v16
	v_add_f32_e32 v16, v16, v16
	v_fmamk_f32 v19, v16, 0x3ab60b61, v213
	v_fmaak_f32 v19, v16, v19, 0x3d2aaaab
	v_fmaak_f32 v19, v16, v19, 0x3e2aaaab
	v_fma_f32 v19, v16, v19, 0.5
	v_fma_f32 v19, v16, v19, 1.0
	v_mul_f32_e64 v16, v19, -v16
	v_cmp_gt_f32_e32 vcc, s31, v16
	v_mul_f32_e32 v19, 0x4f800000, v16
	v_add_f32_e32 v17, 1.0, v17
	v_cndmask_b32_e32 v16, v16, v19, vcc
	v_sqrt_f32_e32 v19, v16
	v_rcp_f32_e32 v17, v17
	v_exp_f32_e32 v18, v18
	v_add_u32_e32 v20, -1, v19
	v_fma_f32 v21, -v20, v19, v16
	v_cmp_ge_f32_e64 s[0:1], 0, v21
	v_add_u32_e32 v21, 1, v19
	s_nop 0
	v_cndmask_b32_e64 v20, v19, v20, s[0:1]
	v_fma_f32 v19, -v21, v19, v16
	v_cmp_lt_f32_e64 s[0:1], 0, v19
	s_nop 1
	v_cndmask_b32_e64 v19, v20, v21, s[0:1]
	v_mul_f32_e32 v20, 0x37800000, v19
	v_cndmask_b32_e32 v19, v19, v20, vcc
	v_cmp_class_f32_e32 vcc, v16, v214
	s_nop 1
	v_cndmask_b32_e32 v16, v19, v16, vcc
	ds_read_b32 v19, v24 offset:9292
	s_waitcnt lgkmcnt(0)
; __device__ __forceinline__ float sigm(float x) { return __builtin_amdgcn_rcpf(1.f + __expf(-x)); }
; __device__ __forceinline__ void mixB1_item(const Params& P, int layer, int idx, const bf16_t* z, float* hsl, float* Pc, float* carryP, float* carryH, char* lds) {
;     ...
;     const int t = 16 * w + fr;
; #pragma unroll
;     for (int jn = 0; jn < 4; ++jn)
; #pragma unroll
;       for (int e = 0; e < 4; ++e) {
;         const int j = jn * 16 + 4 * fq + e, ch = layer * 256 + g * 64 + j;
;         const float r = sigm(ar[jn][e] + P.lru_ba[ch]), ig = sigm(ai[jn][e] + P.lru_bx[ch]);
;         const float lam = P.lru_lam[ch];
;         const float xe = __expf(-lam);
;         float m8; asm volatile("v_mov_b32 %0, 0xc1000000" : "=v"(m8));
;         const float la = m8 * r * (xe * (1.f - xe * (0.5f - xe * (1.f / 3.f))));
;         const float av = __expf(la);
;         const float y2 = 2.f * la;
;         const float om = -y2 * (1.f + y2 * (0.5f + y2 * ((1.f / 6.f) + y2 * ((1.f / 24.f) + y2 * ((1.f / 120.f) + y2 * (1.f / 720.f))))));
;         const float bv = sqrtf(om) * (ig * xcf[t * 65 + j]);
;         aA[t * 65 + j] = av; bB[t * 65 + j] = bv;
;       }
	v_mul_f32_e32 v17, v19, v17
	v_mul_f32_e32 v16, v17, v16
	v_add_u32_e32 v17, 0x4c, v24
	ds_write2st64_b32 v17, v18, v16 offset0:101 offset1:166
	v_mov_b32_e32 v16, v92
	s_waitcnt vmcnt(0)
	v_add_f32_e32 v12, v12, v16
	v_mov_b32_e32 v16, v108
	v_mul_f32_e32 v12, 0xbfb8aa3b, v12
	v_exp_f32_e32 v12, v12
	s_waitcnt vmcnt(0)
	v_add_f32_e32 v8, v8, v16
	v_mov_b32_e32 v16, v124
	v_add_f32_e32 v12, 1.0, v12
	v_rcp_f32_e32 v12, v12
	v_mov_b32 v17, 0xc1000000
	v_mul_f32_e32 v8, 0xbfb8aa3b, v8
	v_exp_f32_e32 v8, v8
	v_mul_f32_e32 v12, v17, v12
	v_add_f32_e32 v8, 1.0, v8
	v_rcp_f32_e32 v8, v8
	s_waitcnt vmcnt(0)
	v_mul_f32_e32 v16, 0xbfb8aa3b, v16
	v_exp_f32_e32 v16, v16
	s_nop 0
	v_fma_f32 v17, v16, s30, 0.5
	v_fma_f32 v17, -v16, v17, 1.0
	v_mul_f32_e32 v16, v16, v17
	v_mul_f32_e32 v12, v12, v16
	v_mul_f32_e32 v16, 0x3fb8aa3b, v12
	v_add_f32_e32 v12, v12, v12
	v_fmamk_f32 v17, v12, 0x3ab60b61, v213
	v_fmaak_f32 v17, v12, v17, 0x3d2aaaab
	v_fmaak_f32 v17, v12, v17, 0x3e2aaaab
	v_fma_f32 v17, v12, v17, 0.5
	v_fma_f32 v17, v12, v17, 1.0
	v_mul_f32_e64 v12, v17, -v12
	v_cmp_gt_f32_e32 vcc, s31, v12
	v_mul_f32_e32 v17, 0x4f800000, v12
	v_exp_f32_e32 v16, v16
	v_cndmask_b32_e32 v12, v12, v17, vcc
	v_sqrt_f32_e32 v17, v12
	s_nop 0
	v_add_u32_e32 v18, -1, v17
	v_fma_f32 v19, -v18, v17, v12
	v_cmp_ge_f32_e64 s[0:1], 0, v19
	v_add_u32_e32 v19, 1, v17
	s_nop 0
	v_cndmask_b32_e64 v18, v17, v18, s[0:1]
	v_fma_f32 v17, -v19, v17, v12
	v_cmp_lt_f32_e64 s[0:1], 0, v17
	s_nop 1
	v_cndmask_b32_e64 v17, v18, v19, s[0:1]
	v_mul_f32_e32 v18, 0x37800000, v17
	v_cndmask_b32_e32 v17, v17, v18, vcc
	v_cmp_class_f32_e32 vcc, v12, v214
	s_nop 1
	v_cndmask_b32_e32 v12, v17, v12, vcc
	ds_read_b32 v17, v24 offset:9344
	s_waitcnt lgkmcnt(0)
	v_mul_f32_e32 v8, v17, v8
	v_mul_f32_e32 v8, v8, v12
	v_add_u32_e32 v12, 0x80, v24
	ds_write2st64_b32 v12, v16, v8 offset0:101 offset1:166
	v_mov_b32_e32 v8, v93
	v_mov_b32_e32 v12, v109
	s_waitcnt vmcnt(1)
	v_add_f32_e32 v8, v13, v8
	s_waitcnt vmcnt(0)
	v_add_f32_e32 v9, v9, v12
	v_mov_b32_e32 v12, v125
	v_mul_f32_e32 v8, 0xbfb8aa3b, v8
	v_exp_f32_e32 v8, v8
	v_mov_b32 v13, 0xc1000000
	v_mul_f32_e32 v9, 0xbfb8aa3b, v9
	v_exp_f32_e32 v9, v9
	v_add_f32_e32 v8, 1.0, v8
	v_rcp_f32_e32 v8, v8
	v_add_f32_e32 v9, 1.0, v9
	v_rcp_f32_e32 v9, v9
	v_mul_f32_e32 v8, v13, v8
	s_waitcnt vmcnt(0)
	v_mul_f32_e32 v12, 0xbfb8aa3b, v12
	v_exp_f32_e32 v12, v12
	s_nop 0
	v_fma_f32 v13, v12, s30, 0.5
	v_fma_f32 v13, -v12, v13, 1.0
	v_mul_f32_e32 v12, v12, v13
	v_mul_f32_e32 v8, v8, v12
	v_mul_f32_e32 v12, 0x3fb8aa3b, v8
	v_add_f32_e32 v8, v8, v8
	v_fmamk_f32 v13, v8, 0x3ab60b61, v213
	v_fmaak_f32 v13, v8, v13, 0x3d2aaaab
	v_fmaak_f32 v13, v8, v13, 0x3e2aaaab
	v_fma_f32 v13, v8, v13, 0.5
	v_fma_f32 v13, v8, v13, 1.0
	v_mul_f32_e64 v8, v13, -v8
	v_cmp_gt_f32_e32 vcc, s31, v8
	v_mul_f32_e32 v13, 0x4f800000, v8
	v_exp_f32_e32 v12, v12
	v_cndmask_b32_e32 v8, v8, v13, vcc
	v_sqrt_f32_e32 v13, v8
	s_nop 0
	v_add_u32_e32 v16, -1, v13
	v_fma_f32 v17, -v16, v13, v8
	v_cmp_ge_f32_e64 s[0:1], 0, v17
	v_add_u32_e32 v17, 1, v13
	s_nop 0
	v_cndmask_b32_e64 v16, v13, v16, s[0:1]
	v_fma_f32 v13, -v17, v13, v8
	v_cmp_lt_f32_e64 s[0:1], 0, v13
	s_nop 1
	v_cndmask_b32_e64 v13, v16, v17, s[0:1]
	v_mul_f32_e32 v16, 0x37800000, v13
	v_cndmask_b32_e32 v13, v13, v16, vcc
	v_cmp_class_f32_e32 vcc, v8, v214
	s_nop 1
	v_cndmask_b32_e32 v8, v13, v8, vcc
	ds_read_b32 v13, v24 offset:9348
	s_waitcnt lgkmcnt(0)
	v_mul_f32_e32 v9, v13, v9
	v_mul_f32_e32 v8, v9, v8
	v_add_u32_e32 v9, 0x84, v24
	ds_write2st64_b32 v9, v12, v8 offset0:101 offset1:166
	v_mov_b32_e32 v8, v94
	v_mov_b32_e32 v9, v110
	s_waitcnt vmcnt(1)
	v_add_f32_e32 v8, v14, v8
	s_waitcnt vmcnt(0)
	v_add_f32_e32 v9, v10, v9
	v_mov_b32_e32 v10, v126
	v_mul_f32_e32 v8, 0xbfb8aa3b, v8
	v_exp_f32_e32 v8, v8
	v_mov_b32 v12, 0xc1000000
	v_mul_f32_e32 v9, 0xbfb8aa3b, v9
	v_exp_f32_e32 v9, v9
	v_add_f32_e32 v8, 1.0, v8
	v_rcp_f32_e32 v8, v8
	v_add_f32_e32 v9, 1.0, v9
	v_rcp_f32_e32 v9, v9
	v_mul_f32_e32 v8, v12, v8
	s_waitcnt vmcnt(0)
	v_mul_f32_e32 v10, 0xbfb8aa3b, v10
	v_exp_f32_e32 v10, v10
	s_nop 0
	v_fma_f32 v12, v10, s30, 0.5
	v_fma_f32 v12, -v10, v12, 1.0
	v_mul_f32_e32 v10, v10, v12
	v_mul_f32_e32 v8, v8, v10
	v_mul_f32_e32 v10, 0x3fb8aa3b, v8
	v_add_f32_e32 v8, v8, v8
	v_fmamk_f32 v12, v8, 0x3ab60b61, v213
	v_fmaak_f32 v12, v8, v12, 0x3d2aaaab
	v_fmaak_f32 v12, v8, v12, 0x3e2aaaab
	v_fma_f32 v12, v8, v12, 0.5
	v_fma_f32 v12, v8, v12, 1.0
	v_mul_f32_e64 v8, v12, -v8
	v_cmp_gt_f32_e32 vcc, s31, v8
	v_mul_f32_e32 v12, 0x4f800000, v8
	v_exp_f32_e32 v10, v10
	v_cndmask_b32_e32 v8, v8, v12, vcc
	v_sqrt_f32_e32 v12, v8
	s_nop 0
	v_add_u32_e32 v13, -1, v12
	v_fma_f32 v14, -v13, v12, v8
	v_cmp_ge_f32_e64 s[0:1], 0, v14
	v_add_u32_e32 v14, 1, v12
	s_nop 0
	v_cndmask_b32_e64 v13, v12, v13, s[0:1]
	v_fma_f32 v12, -v14, v12, v8
	v_cmp_lt_f32_e64 s[0:1], 0, v12
	s_nop 1
	v_cndmask_b32_e64 v12, v13, v14, s[0:1]
	v_mul_f32_e32 v13, 0x37800000, v12
	v_cndmask_b32_e32 v12, v12, v13, vcc
	v_cmp_class_f32_e32 vcc, v8, v214
	s_nop 1
	v_cndmask_b32_e32 v8, v12, v8, vcc
	ds_read_b32 v12, v24 offset:9352
	s_waitcnt lgkmcnt(0)
	v_mul_f32_e32 v9, v12, v9
	v_mul_f32_e32 v8, v9, v8
	v_add_u32_e32 v9, 0x88, v24
	ds_write2st64_b32 v9, v10, v8 offset0:101 offset1:166
	v_mov_b32_e32 v8, v95
	v_mov_b32_e32 v9, v111
	v_mov_b32_e32 v10, v127
	s_waitcnt vmcnt(2)
	v_add_f32_e32 v8, v15, v8
	v_mul_f32_e32 v8, 0xbfb8aa3b, v8
	v_exp_f32_e32 v8, v8
	s_waitcnt vmcnt(0)
; __device__ __forceinline__ float sigm(float x) { return __builtin_amdgcn_rcpf(1.f + __expf(-x)); }
; __device__ __forceinline__ void mixB1_item(const Params& P, int layer, int idx, const bf16_t* z, float* hsl, float* Pc, float* carryP, float* carryH, char* lds) {
;     ...
;     const int t = 16 * w + fr;
; #pragma unroll
;     for (int jn = 0; jn < 4; ++jn)
; #pragma unroll
;       for (int e = 0; e < 4; ++e) {
;         const int j = jn * 16 + 4 * fq + e, ch = layer * 256 + g * 64 + j;
;         const float r = sigm(ar[jn][e] + P.lru_ba[ch]), ig = sigm(ai[jn][e] + P.lru_bx[ch]);
;         const float lam = P.lru_lam[ch];
;         const float xe = __expf(-lam);
;         float m8; asm volatile("v_mov_b32 %0, 0xc1000000" : "=v"(m8));
;         const float la = m8 * r * (xe * (1.f - xe * (0.5f - xe * (1.f / 3.f))));
;         const float av = __expf(la);
;         const float y2 = 2.f * la;
;         const float om = -y2 * (1.f + y2 * (0.5f + y2 * ((1.f / 6.f) + y2 * ((1.f / 24.f) + y2 * ((1.f / 120.f) + y2 * (1.f / 720.f))))));
;         const float bv = sqrtf(om) * (ig * xcf[t * 65 + j]);
;         aA[t * 65 + j] = av; bB[t * 65 + j] = bv;
;       }
	v_mul_f32_e32 v10, 0xbfb8aa3b, v10
	v_exp_f32_e32 v10, v10
	v_add_f32_e32 v9, v11, v9
	v_add_f32_e32 v8, 1.0, v8
	v_rcp_f32_e32 v8, v8
	v_mov_b32 v11, 0xc1000000
	v_mul_f32_e32 v9, 0xbfb8aa3b, v9
	v_exp_f32_e32 v9, v9
	v_mul_f32_e32 v8, v11, v8
	v_fma_f32 v11, v10, s30, 0.5
	v_fma_f32 v11, -v10, v11, 1.0
	v_mul_f32_e32 v10, v10, v11
	v_mul_f32_e32 v8, v8, v10
	v_mul_f32_e32 v10, 0x3fb8aa3b, v8
	v_add_f32_e32 v8, v8, v8
	v_fmamk_f32 v11, v8, 0x3ab60b61, v213
	v_fmaak_f32 v11, v8, v11, 0x3d2aaaab
	v_fmaak_f32 v11, v8, v11, 0x3e2aaaab
	v_fma_f32 v11, v8, v11, 0.5
	v_fma_f32 v11, v8, v11, 1.0
	v_mul_f32_e64 v8, v11, -v8
	v_cmp_gt_f32_e32 vcc, s31, v8
	v_mul_f32_e32 v11, 0x4f800000, v8
	v_add_f32_e32 v9, 1.0, v9
	v_cndmask_b32_e32 v8, v8, v11, vcc
	v_sqrt_f32_e32 v11, v8
	v_rcp_f32_e32 v9, v9
	v_exp_f32_e32 v10, v10
	v_add_u32_e32 v12, -1, v11
	v_fma_f32 v13, -v12, v11, v8
	v_cmp_ge_f32_e64 s[0:1], 0, v13
	v_add_u32_e32 v13, 1, v11
	s_nop 0
	v_cndmask_b32_e64 v12, v11, v12, s[0:1]
	v_fma_f32 v11, -v13, v11, v8
	v_cmp_lt_f32_e64 s[0:1], 0, v11
	s_nop 1
	v_cndmask_b32_e64 v11, v12, v13, s[0:1]
	v_mul_f32_e32 v12, 0x37800000, v11
	v_cndmask_b32_e32 v11, v11, v12, vcc
	v_cmp_class_f32_e32 vcc, v8, v214
	s_nop 1
	v_cndmask_b32_e32 v8, v11, v8, vcc
	ds_read_b32 v11, v24 offset:9356
	s_waitcnt lgkmcnt(0)
	v_mul_f32_e32 v9, v11, v9
	v_mul_f32_e32 v8, v9, v8
	v_add_u32_e32 v9, 0x8c, v24
	ds_write2st64_b32 v9, v10, v8 offset0:101 offset1:166
	v_mov_b32_e32 v8, v96
	s_waitcnt vmcnt(0)
	v_add_f32_e32 v4, v4, v8
	v_mov_b32_e32 v8, v112
	v_mul_f32_e32 v4, 0xbfb8aa3b, v4
	v_exp_f32_e32 v4, v4
	s_waitcnt vmcnt(0)
	v_add_f32_e32 v0, v0, v8
	v_mov_b32_e32 v8, v128
	v_add_f32_e32 v4, 1.0, v4
	v_rcp_f32_e32 v4, v4
	v_mov_b32 v9, 0xc1000000
	v_mul_f32_e32 v0, 0xbfb8aa3b, v0
	v_exp_f32_e32 v0, v0
	v_mul_f32_e32 v4, v9, v4
	v_add_f32_e32 v0, 1.0, v0
	v_rcp_f32_e32 v0, v0
	s_waitcnt vmcnt(0)
	v_mul_f32_e32 v8, 0xbfb8aa3b, v8
	v_exp_f32_e32 v8, v8
	s_nop 0
	v_fma_f32 v9, v8, s30, 0.5
	v_fma_f32 v9, -v8, v9, 1.0
	v_mul_f32_e32 v8, v8, v9
	v_mul_f32_e32 v4, v4, v8
	v_mul_f32_e32 v8, 0x3fb8aa3b, v4
	v_add_f32_e32 v4, v4, v4
	v_fmamk_f32 v9, v4, 0x3ab60b61, v213
	v_fmaak_f32 v9, v4, v9, 0x3d2aaaab
	v_fmaak_f32 v9, v4, v9, 0x3e2aaaab
	v_fma_f32 v9, v4, v9, 0.5
	v_fma_f32 v9, v4, v9, 1.0
	v_mul_f32_e64 v4, v9, -v4
	v_cmp_gt_f32_e32 vcc, s31, v4
	v_mul_f32_e32 v9, 0x4f800000, v4
	v_exp_f32_e32 v8, v8
	v_cndmask_b32_e32 v4, v4, v9, vcc
	v_sqrt_f32_e32 v9, v4
	s_nop 0
	v_add_u32_e32 v10, -1, v9
	v_fma_f32 v11, -v10, v9, v4
	v_cmp_ge_f32_e64 s[0:1], 0, v11
	v_add_u32_e32 v11, 1, v9
	s_nop 0
	v_cndmask_b32_e64 v10, v9, v10, s[0:1]
	v_fma_f32 v9, -v11, v9, v4
	v_cmp_lt_f32_e64 s[0:1], 0, v9
	s_nop 1
	v_cndmask_b32_e64 v9, v10, v11, s[0:1]
	v_mul_f32_e32 v10, 0x37800000, v9
	v_cndmask_b32_e32 v9, v9, v10, vcc
	v_cmp_class_f32_e32 vcc, v4, v214
	s_nop 1
	v_cndmask_b32_e32 v4, v9, v4, vcc
	ds_read_b32 v9, v24 offset:9408
	s_waitcnt lgkmcnt(0)
	v_mul_f32_e32 v0, v9, v0
	v_mul_f32_e32 v0, v0, v4
	v_add_u32_e32 v4, 0xc0, v24
	ds_write2st64_b32 v4, v8, v0 offset0:101 offset1:166
	v_mov_b32_e32 v0, v97
	v_mov_b32_e32 v4, v113
	s_waitcnt vmcnt(1)
	v_add_f32_e32 v0, v5, v0
	s_waitcnt vmcnt(0)
	v_add_f32_e32 v1, v1, v4
	v_mov_b32_e32 v4, v129
	v_mul_f32_e32 v0, 0xbfb8aa3b, v0
	v_exp_f32_e32 v0, v0
	v_mov_b32 v5, 0xc1000000
	v_mul_f32_e32 v1, 0xbfb8aa3b, v1
	v_exp_f32_e32 v1, v1
	v_add_f32_e32 v0, 1.0, v0
	v_rcp_f32_e32 v0, v0
	v_add_f32_e32 v1, 1.0, v1
	v_rcp_f32_e32 v1, v1
	v_mul_f32_e32 v0, v5, v0
	s_waitcnt vmcnt(0)
	v_mul_f32_e32 v4, 0xbfb8aa3b, v4
	v_exp_f32_e32 v4, v4
	s_nop 0
	v_fma_f32 v5, v4, s30, 0.5
	v_fma_f32 v5, -v4, v5, 1.0
	v_mul_f32_e32 v4, v4, v5
	v_mul_f32_e32 v0, v0, v4
	v_mul_f32_e32 v4, 0x3fb8aa3b, v0
	v_add_f32_e32 v0, v0, v0
	v_fmamk_f32 v5, v0, 0x3ab60b61, v213
	v_fmaak_f32 v5, v0, v5, 0x3d2aaaab
	v_fmaak_f32 v5, v0, v5, 0x3e2aaaab
	v_fma_f32 v5, v0, v5, 0.5
	v_fma_f32 v5, v0, v5, 1.0
	v_mul_f32_e64 v0, v5, -v0
	v_cmp_gt_f32_e32 vcc, s31, v0
	v_mul_f32_e32 v5, 0x4f800000, v0
	v_exp_f32_e32 v4, v4
	v_cndmask_b32_e32 v0, v0, v5, vcc
	v_sqrt_f32_e32 v5, v0
	s_nop 0
	v_add_u32_e32 v8, -1, v5
	v_fma_f32 v9, -v8, v5, v0
	v_cmp_ge_f32_e64 s[0:1], 0, v9
	v_add_u32_e32 v9, 1, v5
	s_nop 0
	v_cndmask_b32_e64 v8, v5, v8, s[0:1]
	v_fma_f32 v5, -v9, v5, v0
	v_cmp_lt_f32_e64 s[0:1], 0, v5
	s_nop 1
	v_cndmask_b32_e64 v5, v8, v9, s[0:1]
	v_mul_f32_e32 v8, 0x37800000, v5
	v_cndmask_b32_e32 v5, v5, v8, vcc
	v_cmp_class_f32_e32 vcc, v0, v214
	s_nop 1
	v_cndmask_b32_e32 v0, v5, v0, vcc
	ds_read_b32 v5, v24 offset:9412
	s_waitcnt lgkmcnt(0)
	v_mul_f32_e32 v1, v5, v1
	v_mul_f32_e32 v0, v1, v0
	v_add_u32_e32 v1, 0xc4, v24
	ds_write2st64_b32 v1, v4, v0 offset0:101 offset1:166
	v_mov_b32_e32 v0, v98
	v_mov_b32_e32 v1, v114
	s_waitcnt vmcnt(1)
	v_add_f32_e32 v0, v6, v0
	s_waitcnt vmcnt(0)
	v_add_f32_e32 v1, v2, v1
	v_mov_b32_e32 v2, v130
	v_mul_f32_e32 v0, 0xbfb8aa3b, v0
	v_exp_f32_e32 v0, v0
	v_mov_b32 v4, 0xc1000000
	v_mul_f32_e32 v1, 0xbfb8aa3b, v1
	v_exp_f32_e32 v1, v1
	v_add_f32_e32 v0, 1.0, v0
	v_rcp_f32_e32 v0, v0
	v_add_f32_e32 v1, 1.0, v1
	v_rcp_f32_e32 v1, v1
	v_mul_f32_e32 v0, v4, v0
	s_waitcnt vmcnt(0)
; __device__ __forceinline__ float sigm(float x) { return __builtin_amdgcn_rcpf(1.f + __expf(-x)); }
; __device__ __forceinline__ void mixB1_item(const Params& P, int layer, int idx, const bf16_t* z, float* hsl, float* Pc, float* carryP, float* carryH, char* lds) {
;     ...
;     const int t = 16 * w + fr;
; #pragma unroll
;     for (int jn = 0; jn < 4; ++jn)
; #pragma unroll
;       for (int e = 0; e < 4; ++e) {
;         const int j = jn * 16 + 4 * fq + e, ch = layer * 256 + g * 64 + j;
;         const float r = sigm(ar[jn][e] + P.lru_ba[ch]), ig = sigm(ai[jn][e] + P.lru_bx[ch]);
;         const float lam = P.lru_lam[ch];
;         const float xe = __expf(-lam);
;         float m8; asm volatile("v_mov_b32 %0, 0xc1000000" : "=v"(m8));
;         const float la = m8 * r * (xe * (1.f - xe * (0.5f - xe * (1.f / 3.f))));
;         const float av = __expf(la);
;         const float y2 = 2.f * la;
;         const float om = -y2 * (1.f + y2 * (0.5f + y2 * ((1.f / 6.f) + y2 * ((1.f / 24.f) + y2 * ((1.f / 120.f) + y2 * (1.f / 720.f))))));
;         const float bv = sqrtf(om) * (ig * xcf[t * 65 + j]);
;         aA[t * 65 + j] = av; bB[t * 65 + j] = bv;
;       }
;   }
;   __syncthreads();
;   {
;     const int q = tid >> 6, j = tid & 63;
;     float Pq = 1.f, hq = 0.f;
; #pragma unroll
;     for (int i = 0; i < 16; ++i) { const int t = q * 16 + i; const float av = aA[t * 65 + j], bv = bB[t * 65 + j]; hq = av * hq + bv; Pq *= av; aA[t * 65 + j] = Pq; bB[t * 65 + j] = hq; }
;     sm[q * 64 + j] = Pq; sm[256 + q * 64 + j] = hq;
;     __syncthreads();
;     float Pin = 1.f, Hin = 0.f;
;     for (int qq = 0; qq < q; ++qq) { const float pp = sm[qq * 64 + j], hh = sm[256 + qq * 64 + j]; Hin = pp * Hin + hh; Pin *= pp; }
	v_mul_f32_e32 v2, 0xbfb8aa3b, v2
	v_exp_f32_e32 v2, v2
	s_nop 0
	v_fma_f32 v4, v2, s30, 0.5
	v_fma_f32 v4, -v2, v4, 1.0
	v_mul_f32_e32 v2, v2, v4
	v_mul_f32_e32 v0, v0, v2
	v_mul_f32_e32 v2, 0x3fb8aa3b, v0
	v_add_f32_e32 v0, v0, v0
	v_fmamk_f32 v4, v0, 0x3ab60b61, v213
	v_fmaak_f32 v4, v0, v4, 0x3d2aaaab
	v_fmaak_f32 v4, v0, v4, 0x3e2aaaab
	v_fma_f32 v4, v0, v4, 0.5
	v_fma_f32 v4, v0, v4, 1.0
	v_mul_f32_e64 v0, v4, -v0
	v_cmp_gt_f32_e32 vcc, s31, v0
	v_mul_f32_e32 v4, 0x4f800000, v0
	v_exp_f32_e32 v2, v2
	v_cndmask_b32_e32 v0, v0, v4, vcc
	v_sqrt_f32_e32 v4, v0
	s_nop 0
	v_add_u32_e32 v5, -1, v4
	v_fma_f32 v6, -v5, v4, v0
	v_cmp_ge_f32_e64 s[0:1], 0, v6
	v_add_u32_e32 v6, 1, v4
	s_nop 0
	v_cndmask_b32_e64 v5, v4, v5, s[0:1]
	v_fma_f32 v4, -v6, v4, v0
	v_cmp_lt_f32_e64 s[0:1], 0, v4
	s_nop 1
	v_cndmask_b32_e64 v4, v5, v6, s[0:1]
	v_mul_f32_e32 v5, 0x37800000, v4
	v_cndmask_b32_e32 v4, v4, v5, vcc
	v_cmp_class_f32_e32 vcc, v0, v214
	s_nop 1
	v_cndmask_b32_e32 v0, v4, v0, vcc
	ds_read_b32 v4, v24 offset:9416
	s_waitcnt lgkmcnt(0)
	v_mul_f32_e32 v1, v4, v1
	v_mul_f32_e32 v0, v1, v0
	v_add_u32_e32 v1, 0xc8, v24
	ds_write2st64_b32 v1, v2, v0 offset0:101 offset1:166
	v_mov_b32_e32 v0, v99
	v_mov_b32_e32 v1, v115
	v_mov_b32_e32 v2, v131
	s_waitcnt vmcnt(2)
	v_add_f32_e32 v0, v7, v0
	v_mul_f32_e32 v0, 0xbfb8aa3b, v0
	v_exp_f32_e32 v0, v0
	s_waitcnt vmcnt(0)
	v_mul_f32_e32 v2, 0xbfb8aa3b, v2
	v_exp_f32_e32 v2, v2
	v_add_f32_e32 v1, v3, v1
	v_add_f32_e32 v0, 1.0, v0
	v_rcp_f32_e32 v0, v0
	v_mov_b32 v3, 0xc1000000
	v_mul_f32_e32 v1, 0xbfb8aa3b, v1
	v_exp_f32_e32 v1, v1
	v_mul_f32_e32 v0, v3, v0
	v_fma_f32 v3, v2, s30, 0.5
	v_fma_f32 v3, -v2, v3, 1.0
	v_mul_f32_e32 v2, v2, v3
	v_mul_f32_e32 v0, v0, v2
	v_mul_f32_e32 v2, 0x3fb8aa3b, v0
	v_add_f32_e32 v0, v0, v0
	v_fmamk_f32 v3, v0, 0x3ab60b61, v213
	v_fmaak_f32 v3, v0, v3, 0x3d2aaaab
	v_fmaak_f32 v3, v0, v3, 0x3e2aaaab
	v_fma_f32 v3, v0, v3, 0.5
	v_fma_f32 v3, v0, v3, 1.0
	v_mul_f32_e64 v0, v3, -v0
	v_cmp_gt_f32_e32 vcc, s31, v0
	v_mul_f32_e32 v3, 0x4f800000, v0
	v_add_f32_e32 v1, 1.0, v1
	v_cndmask_b32_e32 v0, v0, v3, vcc
	v_sqrt_f32_e32 v3, v0
	v_rcp_f32_e32 v1, v1
	v_exp_f32_e32 v2, v2
	v_add_u32_e32 v4, -1, v3
	v_fma_f32 v5, -v4, v3, v0
	v_cmp_ge_f32_e64 s[0:1], 0, v5
	v_add_u32_e32 v5, 1, v3
	s_nop 0
	v_cndmask_b32_e64 v4, v3, v4, s[0:1]
	v_fma_f32 v3, -v5, v3, v0
	v_cmp_lt_f32_e64 s[0:1], 0, v3
	s_nop 1
	v_cndmask_b32_e64 v3, v4, v5, s[0:1]
	v_mul_f32_e32 v4, 0x37800000, v3
	v_cndmask_b32_e32 v3, v3, v4, vcc
	v_cmp_class_f32_e32 vcc, v0, v214
	s_movk_i32 s0, 0x410
	s_nop 0
	v_cndmask_b32_e32 v0, v3, v0, vcc
	ds_read_b32 v3, v24 offset:9420
	v_cmp_lt_u32_e32 vcc, 63, v40
	s_waitcnt lgkmcnt(0)
	v_mul_f32_e32 v1, v3, v1
	v_mul_f32_e32 v0, v1, v0
	v_add_u32_e32 v1, 0xcc, v24
	ds_write2st64_b32 v1, v2, v0 offset0:101 offset1:166
	v_mad_u32_u24 v0, v39, s0, v38
	v_lshl_add_u32 v2, v0, 2, v60
	v_add_u32_e32 v3, 0x6400, v2
	v_add_u32_e32 v6, 0xa400, v2
	s_waitcnt lgkmcnt(0)
	s_barrier
	ds_read2_b32 v[0:1], v3 offset0:64 offset1:129
	ds_read2_b32 v[4:5], v6 offset0:128 offset1:193
	v_add_u32_e32 v9, 0xa800, v2
	s_waitcnt lgkmcnt(1)
	v_mul_f32_e32 v8, v0, v1
	s_waitcnt lgkmcnt(0)
	v_fma_f32 v4, 0, v0, v4
	v_fmac_f32_e32 v5, v4, v1
	v_add_u32_e32 v0, 0x6600, v2
	ds_write2_b32 v6, v4, v5 offset0:128 offset1:193
	ds_read2_b32 v[0:1], v0 offset0:66 offset1:131
	ds_read2_b32 v[6:7], v9 offset0:2 offset1:67
	s_waitcnt lgkmcnt(0)
	v_fma_f32 v4, v5, v0, v6
	v_mul_f32_e32 v0, v8, v0
	v_fmac_f32_e32 v7, v4, v1
	ds_write2_b32 v3, v8, v0 offset0:129 offset1:194
	ds_write2_b32 v9, v4, v7 offset0:2 offset1:67
	v_add_u32_e32 v8, 0x6800, v2
	v_mul_f32_e32 v3, v0, v1
	ds_read2_b32 v[0:1], v8 offset0:68 offset1:133
	ds_read2_b32 v[4:5], v9 offset0:132 offset1:197
	s_waitcnt lgkmcnt(0)
	v_fma_f32 v4, v7, v0, v4
	v_mul_f32_e32 v0, v3, v0
	v_fmac_f32_e32 v5, v4, v1
	ds_write2_b32 v8, v3, v0 offset0:3 offset1:68
	v_mul_f32_e32 v3, v0, v1
	ds_write2_b32 v9, v4, v5 offset0:132 offset1:197
	v_add_u32_e32 v0, 0x6a00, v2
	v_add_u32_e32 v9, 0xac00, v2
	ds_read2_b32 v[0:1], v0 offset0:70 offset1:135
	ds_read2_b32 v[6:7], v9 offset0:6 offset1:71
	s_waitcnt lgkmcnt(0)
	v_fma_f32 v4, v5, v0, v6
	v_mul_f32_e32 v0, v3, v0
	v_fmac_f32_e32 v7, v4, v1
	ds_write2_b32 v8, v3, v0 offset0:133 offset1:198
	ds_write2_b32 v9, v4, v7 offset0:6 offset1:71
	v_add_u32_e32 v8, 0x6c00, v2
	v_mul_f32_e32 v3, v0, v1
	ds_read2_b32 v[0:1], v8 offset0:72 offset1:137
	ds_read2_b32 v[4:5], v9 offset0:136 offset1:201
	s_waitcnt lgkmcnt(0)
	v_fma_f32 v4, v7, v0, v4
	v_mul_f32_e32 v0, v3, v0
	v_fmac_f32_e32 v5, v4, v1
	ds_write2_b32 v8, v3, v0 offset0:7 offset1:72
	v_mul_f32_e32 v3, v0, v1
	ds_write2_b32 v9, v4, v5 offset0:136 offset1:201
	v_add_u32_e32 v0, 0x6e00, v2
	v_add_u32_e32 v9, 0xb000, v2
	ds_read2_b32 v[0:1], v0 offset0:74 offset1:139
	ds_read2_b32 v[6:7], v9 offset0:10 offset1:75
	s_waitcnt lgkmcnt(0)
	v_fma_f32 v4, v5, v0, v6
	v_mul_f32_e32 v0, v3, v0
	v_fmac_f32_e32 v7, v4, v1
	ds_write2_b32 v8, v3, v0 offset0:137 offset1:202
	ds_write2_b32 v9, v4, v7 offset0:10 offset1:75
	v_add_u32_e32 v8, 0x7000, v2
	v_mul_f32_e32 v3, v0, v1
	ds_read2_b32 v[4:5], v8 offset0:76 offset1:141
	ds_read2_b32 v[0:1], v9 offset0:140 offset1:205
	s_waitcnt lgkmcnt(0)
	v_fma_f32 v0, v7, v4, v0
	v_fmac_f32_e32 v1, v0, v5
	v_mul_f32_e32 v4, v3, v4
	ds_write2_b32 v9, v0, v1 offset0:140 offset1:205
	v_add_u32_e32 v0, 0x7200, v2
	ds_write2_b32 v8, v3, v4 offset0:11 offset1:76
	v_mul_f32_e32 v3, v4, v5
	ds_read2_b32 v[4:5], v0 offset0:78 offset1:143
	v_add_u32_e32 v0, 0xb400, v2
	ds_read2_b32 v[6:7], v0 offset0:14 offset1:79
	s_waitcnt lgkmcnt(0)
	v_fma_f32 v1, v1, v4, v6
	v_mul_f32_e32 v4, v3, v4
	ds_write2_b32 v8, v3, v4 offset0:141 offset1:206
	v_mul_f32_e32 v3, v4, v5
	v_fmac_f32_e32 v7, v1, v5
	ds_write_b32 v2, v3 offset:29756
	ds_write2_b32 v0, v1, v7 offset0:14 offset1:79
	v_lshl_add_u32 v0, v40, 2, v60
	v_mov_b32_e32 v1, 0
	ds_write2st64_b32 v0, v3, v7 offset0:231 offset1:235
	s_waitcnt lgkmcnt(0)
	s_barrier
	s_and_saveexec_b64 s[0:1], vcc
	s_cbranch_execz .LBB0_566
	v_lshl_add_u32 v3, v38, 2, v34
	v_mov_b32_e32 v28, 1.0
	v_mov_b32_e32 v1, 0
	s_mov_b64 s[30:31], 0
	v_mov_b32_e32 v4, v39

; #define TIDX opaque_tid()
; __device__ __forceinline__ void run_phase(const Params& P, int ph, char* lds) {
;     ...
;       if (layer == 0 && blockIdx.x < 4) {
;         const int t3 = TIDX;
;         if (t3 < 128) { const float* pp_ = (const float*)(ws + OFF_CB1P) + (size_t)blockIdx.x * 16 * 128 + t3; float t = P.cmp_b1[blockIdx.x * 128 + t3];
;           for (int q = 0; q < 16; ++q) t += pp_[q * 128]; ((float*)(ws + OFF_CB1))[blockIdx.x * 128 + t3] = t; }
;       }
.LBB0_570:
	v_readlane_b32 s0, v253, 9
	v_readlane_b32 s16, v254, 61
	v_readlane_b32 s1, v253, 10
	v_readlane_b32 s17, v254, 62
	s_and_b64 s[0:1], s[0:1], s[16:17]
	v_readlane_b32 s46, v252, 57
	s_andn2_b64 vcc, exec, s[0:1]
	v_readlane_b32 s1, v252, 55
	s_mov_b32 s34, s46
	s_cbranch_vccnz .LBB0_574
	s_waitcnt vmcnt(0)
	v_mov_b32 v0, v179
	s_nop 0
	v_cmp_gt_i32_e32 vcc, s15, v0
	s_and_saveexec_b64 s[0:1], vcc
	s_cbranch_execz .LBB0_573
	v_readlane_b32 s16, v253, 13
	v_ashrrev_i32_e32 v1, 31, v0
	v_readlane_b32 s17, v253, 14
	v_readlane_b32 s60, v252, 18
	v_readlane_b32 s70, v252, 28
	v_lshl_add_u64 v[2:3], v[0:1], 2, s[16:17]
	v_readlane_b32 s16, v253, 15
	v_readlane_b32 s71, v252, 29
	v_readlane_b32 s61, v252, 19
	v_add_u32_e32 v176, s16, v0
	v_lshlrev_b64 v[0:1], 2, v[176:177]
	v_lshl_add_u64 v[4:5], s[70:71], 0, v[0:1]
	global_load_dword v4, v[4:5], off
	s_nop 0
	global_load_dword v5, v[2:3], off
	s_movk_i32 s16, 0x1000
	s_movk_i32 s61, 0x1400
	s_movk_i32 s60, 0x7fff
	v_readlane_b32 s62, v252, 20
	v_readlane_b32 s63, v252, 21
	v_readlane_b32 s64, v252, 22
	v_readlane_b32 s65, v252, 23
	v_readlane_b32 s66, v252, 24
	v_readlane_b32 s67, v252, 25
	v_readlane_b32 s68, v252, 26
	v_readlane_b32 s69, v252, 27
	v_readlane_b32 s72, v252, 30
	v_readlane_b32 s73, v252, 31
	v_readlane_b32 s74, v252, 32
	v_readlane_b32 s75, v252, 33
	global_load_dword v6, v[2:3], off offset:512
	global_load_dword v7, v[2:3], off offset:1024
	global_load_dword v8, v[2:3], off offset:1536
	global_load_dword v9, v[2:3], off offset:2048
	global_load_dword v10, v[2:3], off offset:2560
	global_load_dword v11, v[2:3], off offset:3072
	global_load_dword v12, v[2:3], off offset:3584
	v_add_co_u32_e32 v2, vcc, s16, v2
	v_readlane_b32 s16, v253, 7
	s_nop 0
	v_addc_co_u32_e32 v3, vcc, 0, v3, vcc
	v_readlane_b32 s17, v253, 8
	global_load_dword v13, v[2:3], off
	global_load_dword v14, v[2:3], off offset:512
	global_load_dword v15, v[2:3], off offset:1024
	global_load_dword v16, v[2:3], off offset:1536
	global_load_dword v17, v[2:3], off offset:2048
	global_load_dword v18, v[2:3], off offset:2560
	global_load_dword v19, v[2:3], off offset:3072
	global_load_dword v20, v[2:3], off offset:3584
	v_lshl_add_u64 v[0:1], s[16:17], 0, v[0:1]
	s_waitcnt vmcnt(0)
	v_add_f32_e32 v4, v4, v5
	v_add_f32_e32 v4, v4, v6
	v_add_f32_e32 v4, v4, v7
	v_add_f32_e32 v4, v4, v8
	v_add_f32_e32 v4, v4, v9
	v_add_f32_e32 v4, v4, v10
	v_add_f32_e32 v4, v4, v11
	v_add_f32_e32 v4, v4, v12
	v_add_f32_e32 v4, v4, v13
	v_add_f32_e32 v4, v4, v14
	v_add_f32_e32 v4, v4, v15
	v_add_f32_e32 v4, v4, v16
	v_add_f32_e32 v4, v4, v17
	v_add_f32_e32 v4, v4, v18
	v_add_f32_e32 v4, v4, v19
	v_add_f32_e32 v4, v4, v20
	global_store_dword v[0:1], v4, off
